# conv window copy stride 544->576 B so A-fragment ds_read_b128 are bank-conflict free
# speedup vs baseline: 1.0509x; 1.0108x over previous
; #define LAS __attribute__((address_space(3)))
; __device__ __forceinline__ unsigned pk2(float lo, float hi) { const f32x2_t f = {lo, hi}; const bf16x2_t b = __builtin_convertvector(f, bf16x2_t); return __builtin_bit_cast(unsigned, b); }
; __device__ __forceinline__ void conv_item(const Params& P, int slice, int item, LAS unsigned char* lds) {
;     ...
;   const int wave = __builtin_amdgcn_readfirstlane(tid >> 6), lane = tid & 63, chh = wave >> 2, w4 = wave & 3, wm = w4 & 1, wn = (w4 >> 1) ^ chh  , ht = tid & 255, l16 = lane & 15, kc = lane >> 4;
;   const int c = item * 2 + chh;
;   const int L = slice < 4 ? 2048 : 16384, nb = slice < 4 ? 8 : 1, nblk = 128 / nb, nbsh = slice < 4 ? 3 : 0;
;   const u16* hyT = (const u16*)(ws + O_HYT);
;   LAS unsigned char* Zs = lds + chh * ZS_BYTES;
;   LAS unsigned char* Wn = lds + 2 * ZS_BYTES + chh * 2 * CONV_GRP * WIN_BYTES;
;   const float* wsh = P.in[I_WSH]; const float* bsh = P.in[I_BSH];
;   if (tid < 64) *(LAS unsigned*)(lds + CONV_ZERO_OFF + 4 * tid) = 0u;
;   {
;     const u16* row = hyT + (size_t)c * TS; const float w0 = wsh[c], w1 = wsh[3072 + c], w2 = wsh[6144 + c], bb = bsh[c];
; #pragma unroll
;     for (int hh = 0; hh < 2; ++hh) {
;       Sc4Raw zr[4][2];
; #pragma unroll
;       for (int i4 = 0; i4 < 4; ++i4) { const int tok = 8 * (ht + 256 * (4 * hh + i4)); zr[i4][0] = sc4_load(row, tok); zr[i4][1] = sc4_load(row, tok + 4); }
;       __builtin_amdgcn_sched_barrier(0);
; #pragma unroll
;       for (int i4 = 0; i4 < 4; ++i4) {
;         const int tok = 8 * (ht + 256 * (4 * hh + i4));
;         const f32x4 a = sc4_apply(zr[i4][0], tok, L, w0, w1, w2, bb), bq = sc4_apply(zr[i4][1], tok + 4, L, w0, w1, w2, bb);
;         const int Bk = tok >> 7, bs = Bk / nblk;
;         u32x4 o; o.x = pk2(a[0], a[1]); o.y = pk2(a[2], a[3]); o.z = pk2(bq[0], bq[1]); o.w = pk2(bq[2], bq[3]);
;         *(LAS u32x4*)(Zs + Bk * ZBLK + bs * 32 + 2 * (tok & 127)) = o;
.LBB0_382:
	s_cmpk_gt_i32 s2, 0x2ff
	s_mov_b64 s[0:1], -1
	s_cbranch_scc0 .LBB0_523
	v_readlane_b32 s4, v253, 0
	v_readlane_b32 s6, v253, 2
	v_readlane_b32 s7, v253, 3
	s_mov_b64 s[0:1], s[6:7]
	v_mov_b32_e32 v9, v215
	v_readlane_b32 s5, v253, 1
	s_nop 0
	v_readfirstlane_b32 s3, v9
	v_cmp_gt_i32_e32 vcc, 64, v9
	s_and_saveexec_b64 s[4:5], vcc
	v_lshl_add_u32 v0, v9, 2, 0
	v_add_u32_e32 v0, 0x23400, v0
	ds_write_b32 v0, v81
	s_or_b64 exec, exec, s[4:5]
	s_ashr_i32 s4, s3, 8
	s_and_b32 s18, s3, 64
	s_bfe_u32 s3, s3, 0x10007
	s_xor_b32 s8, s3, s4
	s_lshl_b32 s3, s2, 1
	s_add_i32 s3, s3, s4
	s_add_i32 s12, s3, 0xfffffa00
	s_add_u32 s19, s0, 0x1f852000
	s_mul_i32 s16, s4, 0x8a00
	s_mul_i32 s4, s4, 0x9000
	s_addc_u32 s20, s1, 0
	s_add_i32 s3, s4, 0
	s_ashr_i32 s13, s12, 31
	s_add_i32 s21, s16, 0
	s_add_i32 s3, s3, 0x11400
	s_lshl_b64 s[6:7], s[12:13], 15
	s_add_u32 s4, s19, s6
	s_addc_u32 s5, s20, s7
	s_lshl_b64 s[10:11], s[12:13], 2
	s_add_u32 s14, s52, s10
	v_mov_b32_e32 v0, 3
	s_addc_u32 s15, s53, s11
	v_lshlrev_b32_sdwa v42, v0, v9 dst_sel:DWORD dst_unused:UNUSED_PAD src0_sel:DWORD src1_sel:BYTE_0
	v_mov_b32_e32 v0, 4
	s_add_u32 s10, s54, s10
	s_waitcnt lgkmcnt(0)
	v_lshlrev_b32_sdwa v80, v0, v9 dst_sel:DWORD dst_unused:UNUSED_PAD src0_sel:DWORD src1_sel:BYTE_0
	v_max_u32_e32 v0, 1, v42
	s_addc_u32 s11, s55, s11
	v_lshl_add_u64 v[12:13], s[4:5], 0, v[80:81]
	v_lshlrev_b32_e32 v0, 1, v0
	s_movk_i32 s9, 0x1000
	global_load_dword v5, v81, s[14:15]
	global_load_dword v4, v220, s[14:15]
	global_load_dword v6, v221, s[14:15]
	global_load_dword v8, v81, s[10:11]
	global_load_dwordx4 v[18:21], v80, s[4:5]
	global_load_ushort v30, v0, s[4:5] offset:-2
	global_load_ushort v32, v80, s[4:5] offset:8
	global_load_ushort v38, v80, s[4:5] offset:16
	v_add_co_u32_e32 v0, vcc, s9, v12
	s_movk_i32 s9, 0x2000
	s_nop 0
	v_addc_co_u32_e32 v1, vcc, 0, v13, vcc
	v_add_co_u32_e32 v10, vcc, s9, v12
	s_movk_i32 s9, 0x3000
	s_nop 0
	v_addc_co_u32_e32 v11, vcc, 0, v13, vcc
	global_load_dwordx4 v[22:25], v[10:11], off offset:-4096
	global_load_ushort v43, v80, s[4:5] offset:4094
	global_load_ushort v44, v[0:1], off offset:8
	global_load_ushort v45, v[0:1], off offset:16
	global_load_dwordx4 v[26:29], v[10:11], off
	global_load_ushort v46, v[0:1], off offset:4094
	global_load_ushort v47, v[10:11], off offset:8
	global_load_ushort v48, v[10:11], off offset:16
	v_add_co_u32_e32 v14, vcc, s9, v12
	s_movk_i32 s9, 0x4000
	s_nop 0
	v_addc_co_u32_e32 v15, vcc, 0, v13, vcc
	v_add_co_u32_e32 v16, vcc, s9, v12
	s_mov_b32 s17, 0
	s_nop 0
	v_addc_co_u32_e32 v17, vcc, 0, v13, vcc
	global_load_dwordx4 v[0:3], v[16:17], off offset:-4096
	global_load_ushort v49, v[10:11], off offset:4094
	global_load_ushort v50, v[14:15], off offset:8
	global_load_ushort v51, v[14:15], off offset:16
	v_lshlrev_b32_e32 v10, 4, v9
	v_and_b32_e32 v7, 48, v9
	v_and_b32_e32 v11, 0xf0, v10
	s_waitcnt vmcnt(0)
	v_lshlrev_b32_e32 v10, 16, v18
	v_lshlrev_b32_e32 v30, 16, v30
	v_cmp_ne_u32_sdwa vcc, v9, v81 src0_sel:BYTE_0 src1_sel:DWORD
	v_and_b32_e32 v18, 0xffff0000, v18
	v_and_b32_e32 v31, 0xffff0000, v19
	v_cndmask_b32_e32 v33, 0, v30, vcc
	v_lshlrev_b32_e32 v35, 16, v32
	v_lshlrev_b32_e32 v19, 16, v19
	v_mov_b32_e32 v32, v18
	v_mov_b32_e32 v30, v19
	v_pk_mul_f32 v[32:33], v[4:5], v[32:33]
	v_pk_mul_f32 v[36:37], v[4:5], v[30:31] op_sel_hi:[0,1]
	v_pk_fma_f32 v[32:33], v[4:5], v[10:11], v[32:33] op_sel:[0,0,1] op_sel_hi:[1,0,0]
	v_mov_b32_e32 v10, v5
	v_mov_b32_e32 v34, v31
	v_pk_fma_f32 v[32:33], v[6:7], v[18:19], v[32:33] op_sel_hi:[0,1,1]
	v_pk_fma_f32 v[18:19], v[10:11], v[18:19], v[36:37] op_sel_hi:[0,1,1]
	v_pk_fma_f32 v[18:19], v[6:7], v[34:35], v[18:19] op_sel_hi:[0,1,1]
	v_pk_add_f32 v[34:35], v[8:9], v[18:19] op_sel_hi:[0,1]
	v_add_u32_e32 v18, 8, v42
	v_and_b32_e32 v18, s33, v18
	v_and_b32_e32 v19, 0xffff0000, v21
	v_lshlrev_b32_e32 v30, 16, v38
	v_cmp_ne_u32_e32 vcc, 0, v18
	v_and_b32_e32 v39, 16, v21
	v_and_b32_e32 v38, 0xffff0000, v20
	v_lshlrev_b32_e32 v41, 16, v21
	v_lshlrev_b32_e32 v21, 16, v20
	v_mov_b32_e32 v20, v31
	v_cndmask_b32_e32 v37, 0, v30, vcc
	v_pk_mov_b32 v[30:31], v[20:21], v[38:39] op_sel:[1,0]
	v_mov_b32_e32 v18, v41
	v_pk_mul_f32 v[30:31], v[4:5], v[30:31] op_sel_hi:[0,1]
	v_mov_b32_e32 v40, v38
	v_pk_fma_f32 v[20:21], v[10:11], v[20:21], v[30:31] op_sel_hi:[0,1,1]
	v_pk_mul_f32 v[30:31], v[4:5], v[18:19] op_sel_hi:[0,1]
	v_pk_fma_f32 v[30:31], v[10:11], v[40:41], v[30:31] op_sel_hi:[0,1,1]
	v_mov_b32_e32 v36, v19
	v_pk_fma_f32 v[20:21], v[6:7], v[40:41], v[20:21] op_sel_hi:[0,1,1]
	v_pk_fma_f32 v[18:19], v[6:7], v[36:37], v[30:31] op_sel_hi:[0,1,1]
	v_pk_add_f32 v[20:21], v[8:9], v[20:21] op_sel_hi:[0,1]
	v_pk_add_f32 v[30:31], v[8:9], v[18:19] op_sel_hi:[0,1]
	v_bfe_u32 v36, v9, 4, 4
	s_movk_i32 s9, 0x100
	v_pk_add_f32 v[32:33], v[8:9], v[32:33] op_sel_hi:[0,1]
	v_cvt_pk_bf16_f32 v20, v20, v21
	v_cvt_pk_bf16_f32 v21, v30, v31
	v_mul_u32_u24_e32 v30, 0x110, v36
	v_or_b32_sdwa v38, v9, s9 dst_sel:DWORD dst_unused:UNUSED_PAD src0_sel:BYTE_0 src1_sel:DWORD
	v_cvt_pk_bf16_f32 v18, v32, v33
	v_cvt_pk_bf16_f32 v19, v34, v35
	v_add3_u32 v30, s21, v30, v11
	v_lshlrev_b32_e32 v34, 3, v38
	ds_write_b128 v30, v[18:21]
	v_and_b32_e32 v19, s33, v34
	v_lshlrev_b32_e32 v18, 16, v22
	v_lshlrev_b32_e32 v20, 16, v43
	v_cmp_ne_u32_e32 vcc, 0, v19
	v_and_b32_e32 v22, 0xffff0000, v22
	v_and_b32_e32 v21, 0xffff0000, v23
	v_cndmask_b32_e32 v31, 0, v20, vcc
	v_lshlrev_b32_e32 v23, 16, v23
	v_mov_b32_e32 v30, v22
	v_mov_b32_e32 v20, v23
	v_pk_mul_f32 v[30:31], v[4:5], v[30:31]
	v_and_b32_e32 v35, 16, v25
	v_pk_fma_f32 v[18:19], v[4:5], v[18:19], v[30:31] op_sel:[0,0,1] op_sel_hi:[1,0,0]
; #define LAS __attribute__((address_space(3)))
; __device__ __forceinline__ f32x4 sc4_apply(const Sc4Raw& r, int tok, int L, float w0, float w1, float w2, float bb) {
;   const float c0 = lo16(r.v.x), c1 = hi16(r.v.x), c2 = lo16(r.v.y), c3 = hi16(r.v.y);
;   const float pv = ((tok & (L - 1)) == 0) ? 0.f : bf2f(r.pr);
;   const float nx = (((tok + 4) & (L - 1)) == 0) ? 0.f : bf2f(r.nr);
;   f32x4 o; o[0] = w0 * pv + w1 * c0 + w2 * c1 + bb; o[1] = w0 * c0 + w1 * c1 + w2 * c2 + bb; o[2] = w0 * c1 + w1 * c2 + w2 * c3 + bb; o[3] = w0 * c2 + w1 * c3 + w2 * nx + bb;
;   return o;
; }
; __device__ __forceinline__ f32x4 sc4(const u16* row_, int tok, int L, float w0, float w1, float w2, float bb) { const Sc4Raw r = sc4_load(row_, tok); return sc4_apply(r, tok, L, w0, w1, w2, bb); }
; __device__ __forceinline__ void conv_item(const Params& P, int slice, int item, LAS unsigned char* lds) {
;   unsigned char* ws = P.ws; LAUNDER_S(ws); int tid = threadIdx.x; LAUNDER_V(tid);
;   const int wave = __builtin_amdgcn_readfirstlane(tid >> 6), lane = tid & 63, chh = wave >> 2, w4 = wave & 3, wm = w4 & 1, wn = (w4 >> 1) ^ chh  , ht = tid & 255, l16 = lane & 15, kc = lane >> 4;
;   const int c = item * 2 + chh;
;   const int L = slice < 4 ? 2048 : 16384, nb = slice < 4 ? 8 : 1, nblk = 128 / nb, nbsh = slice < 4 ? 3 : 0;
;   const u16* hyT = (const u16*)(ws + O_HYT);
;   LAS unsigned char* Zs = lds + chh * ZS_BYTES;
;   LAS unsigned char* Wn = lds + 2 * ZS_BYTES + chh * 2 * CONV_GRP * WIN_BYTES;
;   const float* wsh = P.in[I_WSH]; const float* bsh = P.in[I_BSH];
;   if (tid < 64) *(LAS unsigned*)(lds + CONV_ZERO_OFF + 4 * tid) = 0u;
;   {
;     const u16* row = hyT + (size_t)c * TS; const float w0 = wsh[c], w1 = wsh[3072 + c], w2 = wsh[6144 + c], bb = bsh[c];
; #pragma unroll
;     for (int hh = 0; hh < 2; ++hh) {
;       Sc4Raw zr[4][2];
; #pragma unroll
;       for (int i4 = 0; i4 < 4; ++i4) { const int tok = 8 * (ht + 256 * (4 * hh + i4)); zr[i4][0] = sc4_load(row, tok); zr[i4][1] = sc4_load(row, tok + 4); }
;       __builtin_amdgcn_sched_barrier(0);
; #pragma unroll
;       for (int i4 = 0; i4 < 4; ++i4) {
;         const int tok = 8 * (ht + 256 * (4 * hh + i4));
;         const f32x4 a = sc4_apply(zr[i4][0], tok, L, w0, w1, w2, bb), bq = sc4_apply(zr[i4][1], tok + 4, L, w0, w1, w2, bb);
;         const int Bk = tok >> 7, bs = Bk / nblk;
	v_pk_mul_f32 v[30:31], v[4:5], v[20:21] op_sel_hi:[0,1]
	v_add_u32_e32 v20, 8, v34
	v_pk_fma_f32 v[18:19], v[6:7], v[22:23], v[18:19] op_sel_hi:[0,1,1]
	v_pk_fma_f32 v[22:23], v[10:11], v[22:23], v[30:31] op_sel_hi:[0,1,1]
	v_and_b32_e32 v31, 0xffff0000, v25
	v_and_b32_e32 v20, s33, v20
	v_and_b32_e32 v34, 0xffff0000, v24
	v_lshlrev_b32_e32 v37, 16, v25
	v_lshlrev_b32_e32 v25, 16, v24
	v_mov_b32_e32 v24, v21
	v_mov_b32_e32 v32, v21
	v_cmp_ne_u32_e32 vcc, 0, v20
	v_pk_mov_b32 v[20:21], v[24:25], v[34:35] op_sel:[1,0]
	v_lshlrev_b32_e32 v33, 16, v44
	v_pk_mul_f32 v[20:21], v[4:5], v[20:21] op_sel_hi:[0,1]
	v_lshlrev_b32_e32 v30, 16, v45
	v_mov_b32_e32 v36, v34
	v_pk_fma_f32 v[20:21], v[10:11], v[24:25], v[20:21] op_sel_hi:[0,1,1]
	v_pk_fma_f32 v[22:23], v[6:7], v[32:33], v[22:23] op_sel_hi:[0,1,1]
	v_cndmask_b32_e32 v33, 0, v30, vcc
	v_mov_b32_e32 v30, v37
	v_pk_fma_f32 v[20:21], v[6:7], v[36:37], v[20:21] op_sel_hi:[0,1,1]
	v_pk_add_f32 v[24:25], v[8:9], v[20:21] op_sel_hi:[0,1]
	v_pk_mul_f32 v[20:21], v[4:5], v[30:31] op_sel_hi:[0,1]
	v_pk_fma_f32 v[20:21], v[10:11], v[36:37], v[20:21] op_sel_hi:[0,1,1]
	v_mov_b32_e32 v32, v31
	v_pk_add_f32 v[18:19], v[8:9], v[18:19] op_sel_hi:[0,1]
	v_pk_fma_f32 v[20:21], v[6:7], v[32:33], v[20:21] op_sel_hi:[0,1,1]
	v_lshrrev_b32_e32 v32, 4, v38
	v_pk_add_f32 v[22:23], v[8:9], v[22:23] op_sel_hi:[0,1]
	v_pk_add_f32 v[30:31], v[8:9], v[20:21] op_sel_hi:[0,1]
	v_lshrrev_b32_e32 v33, s86, v32
	v_cvt_pk_bf16_f32 v20, v18, v19
	v_mov_b32_e32 v18, s21
	v_cvt_pk_bf16_f32 v21, v22, v23
	v_cvt_pk_bf16_f32 v22, v24, v25
	v_mad_u32_u24 v19, v32, s85, v18
	v_lshlrev_b32_e32 v24, 5, v33
	v_cvt_pk_bf16_f32 v23, v30, v31
	v_add3_u32 v19, v19, v24, v11
	s_movk_i32 s9, 0x200
	ds_write_b128 v19, v[20:23]
	v_or_b32_sdwa v19, v9, s9 dst_sel:DWORD dst_unused:UNUSED_PAD src0_sel:BYTE_0 src1_sel:DWORD
	v_lshlrev_b32_e32 v32, 3, v19
	v_and_b32_e32 v21, s33, v32
	v_lshlrev_b32_e32 v20, 16, v26
	v_lshlrev_b32_e32 v22, 16, v46
	v_cmp_ne_u32_e32 vcc, 0, v21
	v_and_b32_e32 v26, 0xffff0000, v26
	v_and_b32_e32 v23, 0xffff0000, v27
	v_cndmask_b32_e32 v25, 0, v22, vcc
	v_lshlrev_b32_e32 v27, 16, v27
	v_mov_b32_e32 v24, v26
	v_mov_b32_e32 v22, v27
	v_pk_mul_f32 v[24:25], v[4:5], v[24:25]
	v_and_b32_e32 v33, 16, v29
	v_pk_fma_f32 v[20:21], v[4:5], v[20:21], v[24:25] op_sel:[0,0,1] op_sel_hi:[1,0,0]
	v_pk_mul_f32 v[24:25], v[4:5], v[22:23] op_sel_hi:[0,1]
	v_add_u32_e32 v22, 8, v32
	v_pk_fma_f32 v[20:21], v[6:7], v[26:27], v[20:21] op_sel_hi:[0,1,1]
	v_pk_fma_f32 v[24:25], v[10:11], v[26:27], v[24:25] op_sel_hi:[0,1,1]
	v_and_b32_e32 v27, 0xffff0000, v29
	v_and_b32_e32 v22, s33, v22
	v_and_b32_e32 v32, 0xffff0000, v28
	v_lshlrev_b32_e32 v35, 16, v29
	v_lshlrev_b32_e32 v29, 16, v28
	v_mov_b32_e32 v28, v23
	v_lshlrev_b32_e32 v31, 16, v47
	v_mov_b32_e32 v30, v23
	v_lshlrev_b32_e32 v26, 16, v48
	v_cmp_ne_u32_e32 vcc, 0, v22
	v_pk_mov_b32 v[22:23], v[28:29], v[32:33] op_sel:[1,0]
	v_pk_fma_f32 v[24:25], v[6:7], v[30:31], v[24:25] op_sel_hi:[0,1,1]
	v_cndmask_b32_e32 v31, 0, v26, vcc
	v_mov_b32_e32 v26, v35
	v_pk_mul_f32 v[22:23], v[4:5], v[22:23] op_sel_hi:[0,1]
	v_mov_b32_e32 v34, v32
	v_pk_fma_f32 v[22:23], v[10:11], v[28:29], v[22:23] op_sel_hi:[0,1,1]
	v_pk_mul_f32 v[28:29], v[4:5], v[26:27] op_sel_hi:[0,1]
	v_pk_fma_f32 v[28:29], v[10:11], v[34:35], v[28:29] op_sel_hi:[0,1,1]
	v_mov_b32_e32 v30, v27
	v_lshrrev_b32_e32 v19, 4, v19
	v_pk_add_f32 v[20:21], v[8:9], v[20:21] op_sel_hi:[0,1]
	v_pk_add_f32 v[24:25], v[8:9], v[24:25] op_sel_hi:[0,1]
	v_pk_fma_f32 v[22:23], v[6:7], v[34:35], v[22:23] op_sel_hi:[0,1,1]
	v_pk_fma_f32 v[26:27], v[6:7], v[30:31], v[28:29] op_sel_hi:[0,1,1]
	v_lshrrev_b32_e32 v28, s86, v19
	v_pk_add_f32 v[22:23], v[8:9], v[22:23] op_sel_hi:[0,1]
	v_pk_add_f32 v[26:27], v[8:9], v[26:27] op_sel_hi:[0,1]
	v_cvt_pk_bf16_f32 v20, v20, v21
	v_cvt_pk_bf16_f32 v21, v24, v25
	v_mad_u32_u24 v19, v19, s85, v18
	v_lshlrev_b32_e32 v24, 5, v28
	v_cvt_pk_bf16_f32 v22, v22, v23
	v_cvt_pk_bf16_f32 v23, v26, v27
	v_add3_u32 v19, v19, v24, v11
	s_movk_i32 s9, 0x300
	ds_write_b128 v19, v[20:23]
	v_or_b32_sdwa v19, v9, s9 dst_sel:DWORD dst_unused:UNUSED_PAD src0_sel:BYTE_0 src1_sel:DWORD
	v_lshlrev_b32_e32 v28, 3, v19
	v_and_b32_e32 v21, s33, v28
	v_lshlrev_b32_e32 v20, 16, v0
	v_lshlrev_b32_e32 v22, 16, v49
	v_cmp_ne_u32_e32 vcc, 0, v21
	v_and_b32_e32 v0, 0xffff0000, v0
	v_and_b32_e32 v23, 0xffff0000, v1
	v_cndmask_b32_e32 v25, 0, v22, vcc
	v_lshlrev_b32_e32 v1, 16, v1
	v_mov_b32_e32 v24, v0
	v_mov_b32_e32 v22, v1
	v_pk_mul_f32 v[24:25], v[4:5], v[24:25]
	v_lshlrev_b32_e32 v27, 16, v50
	v_pk_fma_f32 v[20:21], v[4:5], v[20:21], v[24:25] op_sel:[0,0,1] op_sel_hi:[1,0,0]
	v_pk_mul_f32 v[24:25], v[4:5], v[22:23] op_sel_hi:[0,1]
	v_mov_b32_e32 v26, v23
	v_pk_fma_f32 v[20:21], v[6:7], v[0:1], v[20:21] op_sel_hi:[0,1,1]
	v_pk_fma_f32 v[0:1], v[10:11], v[0:1], v[24:25] op_sel_hi:[0,1,1]
	v_pk_fma_f32 v[0:1], v[6:7], v[26:27], v[0:1] op_sel_hi:[0,1,1]
	v_pk_add_f32 v[24:25], v[8:9], v[0:1] op_sel_hi:[0,1]
	v_add_u32_e32 v0, 8, v28
	v_and_b32_e32 v0, s33, v0
	v_and_b32_e32 v1, 0xffff0000, v3
	v_lshlrev_b32_e32 v22, 16, v51
	v_cmp_ne_u32_e32 vcc, 0, v0
	v_and_b32_e32 v29, 16, v3
	v_and_b32_e32 v28, 0xffff0000, v2
	v_lshlrev_b32_e32 v31, 16, v3
	v_lshlrev_b32_e32 v3, 16, v2
	v_mov_b32_e32 v2, v23
	v_cndmask_b32_e32 v27, 0, v22, vcc
	v_pk_mov_b32 v[22:23], v[2:3], v[28:29] op_sel:[1,0]
	v_mov_b32_e32 v0, v31
	v_pk_mul_f32 v[22:23], v[4:5], v[22:23] op_sel_hi:[0,1]
	v_mov_b32_e32 v30, v28
	v_pk_fma_f32 v[2:3], v[10:11], v[2:3], v[22:23] op_sel_hi:[0,1,1]
	v_pk_mul_f32 v[22:23], v[4:5], v[0:1] op_sel_hi:[0,1]
	v_pk_fma_f32 v[22:23], v[10:11], v[30:31], v[22:23] op_sel_hi:[0,1,1]
; #define LAS __attribute__((address_space(3)))
; __device__ __forceinline__ f32x4 sc4_apply(const Sc4Raw& r, int tok, int L, float w0, float w1, float w2, float bb) {
;   const float c0 = lo16(r.v.x), c1 = hi16(r.v.x), c2 = lo16(r.v.y), c3 = hi16(r.v.y);
;   const float pv = ((tok & (L - 1)) == 0) ? 0.f : bf2f(r.pr);
;   const float nx = (((tok + 4) & (L - 1)) == 0) ? 0.f : bf2f(r.nr);
;   f32x4 o; o[0] = w0 * pv + w1 * c0 + w2 * c1 + bb; o[1] = w0 * c0 + w1 * c1 + w2 * c2 + bb; o[2] = w0 * c1 + w1 * c2 + w2 * c3 + bb; o[3] = w0 * c2 + w1 * c3 + w2 * nx + bb;
;   return o;
; }
; __device__ __forceinline__ f32x4 sc4(const u16* row_, int tok, int L, float w0, float w1, float w2, float bb) { const Sc4Raw r = sc4_load(row_, tok); return sc4_apply(r, tok, L, w0, w1, w2, bb); }
; __device__ __forceinline__ void conv_item(const Params& P, int slice, int item, LAS unsigned char* lds) {
;   unsigned char* ws = P.ws; LAUNDER_S(ws); int tid = threadIdx.x; LAUNDER_V(tid);
;   const int wave = __builtin_amdgcn_readfirstlane(tid >> 6), lane = tid & 63, chh = wave >> 2, w4 = wave & 3, wm = w4 & 1, wn = (w4 >> 1) ^ chh  , ht = tid & 255, l16 = lane & 15, kc = lane >> 4;
;   const int c = item * 2 + chh;
;   const int L = slice < 4 ? 2048 : 16384, nb = slice < 4 ? 8 : 1, nblk = 128 / nb, nbsh = slice < 4 ? 3 : 0;
;   const u16* hyT = (const u16*)(ws + O_HYT);
;   LAS unsigned char* Zs = lds + chh * ZS_BYTES;
;   LAS unsigned char* Wn = lds + 2 * ZS_BYTES + chh * 2 * CONV_GRP * WIN_BYTES;
;   const float* wsh = P.in[I_WSH]; const float* bsh = P.in[I_BSH];
;   if (tid < 64) *(LAS unsigned*)(lds + CONV_ZERO_OFF + 4 * tid) = 0u;
;   {
;     const u16* row = hyT + (size_t)c * TS; const float w0 = wsh[c], w1 = wsh[3072 + c], w2 = wsh[6144 + c], bb = bsh[c];
; #pragma unroll
;     for (int hh = 0; hh < 2; ++hh) {
;       Sc4Raw zr[4][2];
; #pragma unroll
;       for (int i4 = 0; i4 < 4; ++i4) { const int tok = 8 * (ht + 256 * (4 * hh + i4)); zr[i4][0] = sc4_load(row, tok); zr[i4][1] = sc4_load(row, tok + 4); }
;       __builtin_amdgcn_sched_barrier(0);
; #pragma unroll
;       for (int i4 = 0; i4 < 4; ++i4) {
;         const int tok = 8 * (ht + 256 * (4 * hh + i4));
;         const f32x4 a = sc4_apply(zr[i4][0], tok, L, w0, w1, w2, bb), bq = sc4_apply(zr[i4][1], tok + 4, L, w0, w1, w2, bb);
;         const int Bk = tok >> 7, bs = Bk / nblk;
	v_mov_b32_e32 v26, v1
	v_lshrrev_b32_e32 v19, 4, v19
	v_pk_add_f32 v[20:21], v[8:9], v[20:21] op_sel_hi:[0,1]
	v_pk_fma_f32 v[2:3], v[6:7], v[30:31], v[2:3] op_sel_hi:[0,1,1]
	v_pk_fma_f32 v[0:1], v[6:7], v[26:27], v[22:23] op_sel_hi:[0,1,1]
	v_lshrrev_b32_e32 v26, s86, v19
	v_pk_add_f32 v[2:3], v[8:9], v[2:3] op_sel_hi:[0,1]
	v_pk_add_f32 v[22:23], v[8:9], v[0:1] op_sel_hi:[0,1]
	v_cvt_pk_bf16_f32 v0, v20, v21
	v_mad_u32_u24 v19, v19, s85, v18
	v_lshlrev_b32_e32 v20, 5, v26
	v_cvt_pk_bf16_f32 v1, v24, v25
	v_cvt_pk_bf16_f32 v2, v2, v3
	v_cvt_pk_bf16_f32 v3, v22, v23
	v_add3_u32 v19, v19, v20, v11
	ds_write_b128 v19, v[0:3]
	s_movk_i32 s9, 0x5000
	v_add_co_u32_e32 v0, vcc, s9, v12
	s_movk_i32 s9, 0x6000
	s_nop 0
	v_addc_co_u32_e32 v1, vcc, 0, v13, vcc
	v_add_co_u32_e32 v2, vcc, s9, v12
	s_movk_i32 s9, 0x7000
	s_nop 0
	v_addc_co_u32_e32 v3, vcc, 0, v13, vcc
	global_load_dwordx4 v[20:23], v[16:17], off
	global_load_ushort v19, v[16:17], off offset:8
	global_load_ushort v34, v[16:17], off offset:16
	global_load_ushort v38, v[16:17], off offset:4094
	global_load_dwordx4 v[24:27], v[2:3], off offset:-4096
	global_load_dwordx4 v[28:31], v[2:3], off
	s_nop 0
	global_load_ushort v14, v[14:15], off offset:4094
	s_nop 0
	global_load_ushort v39, v[0:1], off offset:8
	global_load_ushort v40, v[0:1], off offset:16
	global_load_ushort v41, v[0:1], off offset:4094
	v_add_co_u32_e32 v12, vcc, s9, v12
	v_or_b32_e32 v0, 0x3804, v42
	s_nop 0
	v_addc_co_u32_e32 v13, vcc, 0, v13, vcc
	v_min_u32_e32 v0, 0x3ffb, v0
	global_load_ushort v43, v[2:3], off offset:8
	global_load_ushort v44, v[2:3], off offset:16
	global_load_ushort v45, v[2:3], off offset:4094
	v_lshlrev_b32_e32 v15, 1, v0
	global_load_dwordx4 v[0:3], v[12:13], off
	global_load_ushort v42, v[12:13], off offset:8
	global_load_ushort v46, v15, s[4:5] offset:8
	s_movk_i32 s4, 0x400
	v_or_b32_sdwa v47, v9, s4 dst_sel:DWORD dst_unused:UNUSED_PAD src0_sel:BYTE_0 src1_sel:DWORD
	v_lshlrev_b32_e32 v35, 3, v47
	v_and_b32_e32 v13, s33, v35
	s_waitcnt vmcnt(15)
	v_lshlrev_b32_e32 v12, 16, v20
	s_waitcnt vmcnt(9)
	v_lshlrev_b32_e32 v14, 16, v14
	v_cmp_ne_u32_e32 vcc, 0, v13
	v_and_b32_e32 v20, 0xffff0000, v20
	v_and_b32_e32 v15, 0xffff0000, v21
	v_cndmask_b32_e32 v17, 0, v14, vcc
	v_lshlrev_b32_e32 v21, 16, v21
	v_mov_b32_e32 v16, v20
	v_mov_b32_e32 v14, v21
	v_pk_mul_f32 v[16:17], v[4:5], v[16:17]
	v_lshlrev_b32_e32 v33, 16, v19
	v_pk_fma_f32 v[12:13], v[4:5], v[12:13], v[16:17] op_sel:[0,0,1] op_sel_hi:[1,0,0]
	v_pk_mul_f32 v[16:17], v[4:5], v[14:15] op_sel_hi:[0,1]
	v_add_u32_e32 v14, 8, v35
	v_pk_fma_f32 v[12:13], v[6:7], v[20:21], v[12:13] op_sel_hi:[0,1,1]
	v_pk_fma_f32 v[16:17], v[10:11], v[20:21], v[16:17] op_sel_hi:[0,1,1]
	v_and_b32_e32 v21, 0xffff0000, v23
	v_and_b32_e32 v14, s33, v14
	v_lshlrev_b32_e32 v19, 16, v34
	v_and_b32_e32 v35, 16, v23
	v_and_b32_e32 v34, 0xffff0000, v22
	v_lshlrev_b32_e32 v37, 16, v23
	v_lshlrev_b32_e32 v23, 16, v22
	v_mov_b32_e32 v22, v15
	v_mov_b32_e32 v32, v15
	v_cmp_ne_u32_e32 vcc, 0, v14
	v_pk_mov_b32 v[14:15], v[22:23], v[34:35] op_sel:[1,0]
	v_mov_b32_e32 v20, v37
	v_pk_mul_f32 v[14:15], v[4:5], v[14:15] op_sel_hi:[0,1]
	v_mov_b32_e32 v36, v34
	v_pk_fma_f32 v[14:15], v[10:11], v[22:23], v[14:15] op_sel_hi:[0,1,1]
	v_pk_mul_f32 v[22:23], v[4:5], v[20:21] op_sel_hi:[0,1]
	v_pk_fma_f32 v[16:17], v[6:7], v[32:33], v[16:17] op_sel_hi:[0,1,1]
	v_cndmask_b32_e32 v33, 0, v19, vcc
	v_pk_fma_f32 v[22:23], v[10:11], v[36:37], v[22:23] op_sel_hi:[0,1,1]
	v_mov_b32_e32 v32, v21
	v_lshrrev_b32_e32 v19, 4, v47
	v_pk_add_f32 v[12:13], v[8:9], v[12:13] op_sel_hi:[0,1]
	v_pk_add_f32 v[16:17], v[8:9], v[16:17] op_sel_hi:[0,1]
	v_pk_fma_f32 v[14:15], v[6:7], v[36:37], v[14:15] op_sel_hi:[0,1,1]
	v_pk_fma_f32 v[20:21], v[6:7], v[32:33], v[22:23] op_sel_hi:[0,1,1]
	v_lshrrev_b32_e32 v22, s86, v19
	s_movk_i32 s4, 0x500
	v_pk_add_f32 v[14:15], v[8:9], v[14:15] op_sel_hi:[0,1]
	v_pk_add_f32 v[20:21], v[8:9], v[20:21] op_sel_hi:[0,1]
	v_cvt_pk_bf16_f32 v12, v12, v13
	v_cvt_pk_bf16_f32 v13, v16, v17
	v_mad_u32_u24 v16, v19, s85, v18
	v_lshlrev_b32_e32 v17, 5, v22
	v_or_b32_sdwa v19, v9, s4 dst_sel:DWORD dst_unused:UNUSED_PAD src0_sel:BYTE_0 src1_sel:DWORD
	v_cvt_pk_bf16_f32 v14, v14, v15
	v_cvt_pk_bf16_f32 v15, v20, v21
	v_add3_u32 v16, v16, v17, v11
	v_lshlrev_b32_e32 v32, 3, v19
	ds_write_b128 v16, v[12:15]
	v_and_b32_e32 v13, s33, v32
	v_lshlrev_b32_e32 v14, 16, v38
	v_cmp_ne_u32_e32 vcc, 0, v13
	v_and_b32_e32 v22, 0xffff0000, v24
	v_lshlrev_b32_e32 v23, 16, v25
	v_cndmask_b32_e32 v17, 0, v14, vcc
	v_mov_b32_e32 v16, v22
	v_lshlrev_b32_e32 v12, 16, v24
	v_and_b32_e32 v15, 0xffff0000, v25
	v_mov_b32_e32 v14, v23
	v_pk_mul_f32 v[16:17], v[4:5], v[16:17]
	s_waitcnt vmcnt(8)
	v_lshlrev_b32_e32 v21, 16, v39
	v_pk_fma_f32 v[12:13], v[4:5], v[12:13], v[16:17] op_sel:[0,0,1] op_sel_hi:[1,0,0]
	v_pk_mul_f32 v[16:17], v[4:5], v[14:15] op_sel_hi:[0,1]
	v_add_u32_e32 v14, 8, v32
	v_mov_b32_e32 v20, v15
	v_pk_fma_f32 v[16:17], v[10:11], v[22:23], v[16:17] op_sel_hi:[0,1,1]
	v_and_b32_e32 v14, s33, v14
	v_pk_fma_f32 v[16:17], v[6:7], v[20:21], v[16:17] op_sel_hi:[0,1,1]
	v_and_b32_e32 v21, 0xffff0000, v27
	s_waitcnt vmcnt(7)
; #define LAS __attribute__((address_space(3)))
; __device__ __forceinline__ f32x4 sc4_apply(const Sc4Raw& r, int tok, int L, float w0, float w1, float w2, float bb) {
;   const float c0 = lo16(r.v.x), c1 = hi16(r.v.x), c2 = lo16(r.v.y), c3 = hi16(r.v.y);
;   const float pv = ((tok & (L - 1)) == 0) ? 0.f : bf2f(r.pr);
;   const float nx = (((tok + 4) & (L - 1)) == 0) ? 0.f : bf2f(r.nr);
;   f32x4 o; o[0] = w0 * pv + w1 * c0 + w2 * c1 + bb; o[1] = w0 * c0 + w1 * c1 + w2 * c2 + bb; o[2] = w0 * c1 + w1 * c2 + w2 * c3 + bb; o[3] = w0 * c2 + w1 * c3 + w2 * nx + bb;
;   return o;
; }
; __device__ __forceinline__ f32x4 sc4(const u16* row_, int tok, int L, float w0, float w1, float w2, float bb) { const Sc4Raw r = sc4_load(row_, tok); return sc4_apply(r, tok, L, w0, w1, w2, bb); }
; __device__ __forceinline__ void conv_item(const Params& P, int slice, int item, LAS unsigned char* lds) {
;   unsigned char* ws = P.ws; LAUNDER_S(ws); int tid = threadIdx.x; LAUNDER_V(tid);
;   const int wave = __builtin_amdgcn_readfirstlane(tid >> 6), lane = tid & 63, chh = wave >> 2, w4 = wave & 3, wm = w4 & 1, wn = (w4 >> 1) ^ chh  , ht = tid & 255, l16 = lane & 15, kc = lane >> 4;
;   const int c = item * 2 + chh;
;   const int L = slice < 4 ? 2048 : 16384, nb = slice < 4 ? 8 : 1, nblk = 128 / nb, nbsh = slice < 4 ? 3 : 0;
;   const u16* hyT = (const u16*)(ws + O_HYT);
;   LAS unsigned char* Zs = lds + chh * ZS_BYTES;
;   LAS unsigned char* Wn = lds + 2 * ZS_BYTES + chh * 2 * CONV_GRP * WIN_BYTES;
;   const float* wsh = P.in[I_WSH]; const float* bsh = P.in[I_BSH];
;   if (tid < 64) *(LAS unsigned*)(lds + CONV_ZERO_OFF + 4 * tid) = 0u;
;   {
;     const u16* row = hyT + (size_t)c * TS; const float w0 = wsh[c], w1 = wsh[3072 + c], w2 = wsh[6144 + c], bb = bsh[c];
; #pragma unroll
;     for (int hh = 0; hh < 2; ++hh) {
;       Sc4Raw zr[4][2];
; #pragma unroll
;       for (int i4 = 0; i4 < 4; ++i4) { const int tok = 8 * (ht + 256 * (4 * hh + i4)); zr[i4][0] = sc4_load(row, tok); zr[i4][1] = sc4_load(row, tok + 4); }
;       __builtin_amdgcn_sched_barrier(0);
; #pragma unroll
;       for (int i4 = 0; i4 < 4; ++i4) {
;         const int tok = 8 * (ht + 256 * (4 * hh + i4));
;         const f32x4 a = sc4_apply(zr[i4][0], tok, L, w0, w1, w2, bb), bq = sc4_apply(zr[i4][1], tok + 4, L, w0, w1, w2, bb);
;         const int Bk = tok >> 7, bs = Bk / nblk;
	v_lshlrev_b32_e32 v20, 16, v40
	v_cmp_ne_u32_e32 vcc, 0, v14
	v_and_b32_e32 v25, 16, v27
	v_and_b32_e32 v24, 0xffff0000, v26
	v_lshlrev_b32_e32 v33, 16, v27
	v_lshlrev_b32_e32 v27, 16, v26
	v_mov_b32_e32 v26, v15
	v_pk_fma_f32 v[12:13], v[6:7], v[22:23], v[12:13] op_sel_hi:[0,1,1]
	v_cndmask_b32_e32 v23, 0, v20, vcc
	v_mov_b32_e32 v20, v33
	v_pk_mov_b32 v[14:15], v[26:27], v[24:25] op_sel:[1,0]
	v_mov_b32_e32 v32, v24
	v_pk_mul_f32 v[14:15], v[4:5], v[14:15] op_sel_hi:[0,1]
	v_pk_mul_f32 v[24:25], v[4:5], v[20:21] op_sel_hi:[0,1]
	v_pk_fma_f32 v[14:15], v[10:11], v[26:27], v[14:15] op_sel_hi:[0,1,1]
	v_pk_fma_f32 v[24:25], v[10:11], v[32:33], v[24:25] op_sel_hi:[0,1,1]
	v_mov_b32_e32 v22, v21
	v_lshrrev_b32_e32 v19, 4, v19
	v_pk_add_f32 v[12:13], v[8:9], v[12:13] op_sel_hi:[0,1]
	v_pk_add_f32 v[16:17], v[8:9], v[16:17] op_sel_hi:[0,1]
	v_pk_fma_f32 v[14:15], v[6:7], v[32:33], v[14:15] op_sel_hi:[0,1,1]
	v_pk_fma_f32 v[20:21], v[6:7], v[22:23], v[24:25] op_sel_hi:[0,1,1]
	v_lshrrev_b32_e32 v22, s86, v19
	s_movk_i32 s4, 0x600
	v_pk_add_f32 v[14:15], v[8:9], v[14:15] op_sel_hi:[0,1]
	v_pk_add_f32 v[20:21], v[8:9], v[20:21] op_sel_hi:[0,1]
	v_cvt_pk_bf16_f32 v12, v12, v13
	v_cvt_pk_bf16_f32 v13, v16, v17
	v_mad_u32_u24 v16, v19, s85, v18
	v_lshlrev_b32_e32 v17, 5, v22
	v_or_b32_sdwa v19, v9, s4 dst_sel:DWORD dst_unused:UNUSED_PAD src0_sel:BYTE_0 src1_sel:DWORD
	v_cvt_pk_bf16_f32 v14, v14, v15
	v_cvt_pk_bf16_f32 v15, v20, v21
	v_add3_u32 v16, v16, v17, v11
	v_lshlrev_b32_e32 v24, 3, v19
	ds_write_b128 v16, v[12:15]
	v_and_b32_e32 v13, s33, v24
	s_waitcnt vmcnt(6)
	v_lshlrev_b32_e32 v14, 16, v41
	v_cmp_ne_u32_e32 vcc, 0, v13
	v_and_b32_e32 v22, 0xffff0000, v28
	v_lshlrev_b32_e32 v23, 16, v29
	v_cndmask_b32_e32 v17, 0, v14, vcc
	v_mov_b32_e32 v16, v22
	v_lshlrev_b32_e32 v12, 16, v28
	v_and_b32_e32 v15, 0xffff0000, v29
	v_mov_b32_e32 v14, v23
	v_pk_mul_f32 v[16:17], v[4:5], v[16:17]
	s_waitcnt vmcnt(5)
	v_lshlrev_b32_e32 v21, 16, v43
	v_pk_fma_f32 v[12:13], v[4:5], v[12:13], v[16:17] op_sel:[0,0,1] op_sel_hi:[1,0,0]
	v_pk_mul_f32 v[16:17], v[4:5], v[14:15] op_sel_hi:[0,1]
	v_add_u32_e32 v14, 8, v24
	v_mov_b32_e32 v20, v15
	v_pk_fma_f32 v[16:17], v[10:11], v[22:23], v[16:17] op_sel_hi:[0,1,1]
	v_and_b32_e32 v14, s33, v14
	v_pk_fma_f32 v[16:17], v[6:7], v[20:21], v[16:17] op_sel_hi:[0,1,1]
	s_waitcnt vmcnt(4)
	v_lshlrev_b32_e32 v20, 16, v44
	v_cmp_ne_u32_e32 vcc, 0, v14
	v_and_b32_e32 v25, 16, v31
	v_and_b32_e32 v24, 0xffff0000, v30
	v_lshlrev_b32_e32 v27, 16, v31
	v_lshlrev_b32_e32 v29, 16, v30
	v_mov_b32_e32 v28, v15
	v_pk_fma_f32 v[12:13], v[6:7], v[22:23], v[12:13] op_sel_hi:[0,1,1]
	v_and_b32_e32 v21, 0xffff0000, v31
	v_cndmask_b32_e32 v23, 0, v20, vcc
	v_mov_b32_e32 v20, v27
	v_pk_mov_b32 v[14:15], v[28:29], v[24:25] op_sel:[1,0]
	v_mov_b32_e32 v26, v24
	v_pk_mul_f32 v[14:15], v[4:5], v[14:15] op_sel_hi:[0,1]
	v_pk_mul_f32 v[24:25], v[4:5], v[20:21] op_sel_hi:[0,1]
	v_pk_fma_f32 v[14:15], v[10:11], v[28:29], v[14:15] op_sel_hi:[0,1,1]
	v_pk_fma_f32 v[24:25], v[10:11], v[26:27], v[24:25] op_sel_hi:[0,1,1]
	v_mov_b32_e32 v22, v21
	v_lshrrev_b32_e32 v19, 4, v19
	v_pk_add_f32 v[12:13], v[8:9], v[12:13] op_sel_hi:[0,1]
	v_pk_add_f32 v[16:17], v[8:9], v[16:17] op_sel_hi:[0,1]
	v_pk_fma_f32 v[14:15], v[6:7], v[26:27], v[14:15] op_sel_hi:[0,1,1]
	v_pk_fma_f32 v[20:21], v[6:7], v[22:23], v[24:25] op_sel_hi:[0,1,1]
	v_lshrrev_b32_e32 v22, s86, v19
	s_movk_i32 s4, 0x700
	v_pk_add_f32 v[14:15], v[8:9], v[14:15] op_sel_hi:[0,1]
	v_pk_add_f32 v[20:21], v[8:9], v[20:21] op_sel_hi:[0,1]
	v_cvt_pk_bf16_f32 v12, v12, v13
	v_cvt_pk_bf16_f32 v13, v16, v17
	v_mad_u32_u24 v16, v19, s85, v18
	v_lshlrev_b32_e32 v17, 5, v22
	v_or_b32_sdwa v19, v9, s4 dst_sel:DWORD dst_unused:UNUSED_PAD src0_sel:BYTE_0 src1_sel:DWORD
	v_cvt_pk_bf16_f32 v14, v14, v15
	v_cvt_pk_bf16_f32 v15, v20, v21
	v_add3_u32 v16, v16, v17, v11
	v_lshlrev_b32_e32 v22, 3, v19
	ds_write_b128 v16, v[12:15]
	v_and_b32_e32 v13, s33, v22
	s_waitcnt vmcnt(2)
	v_lshlrev_b32_e32 v12, 16, v0
	v_lshlrev_b32_e32 v14, 16, v45
	v_cmp_ne_u32_e32 vcc, 0, v13
	v_and_b32_e32 v0, 0xffff0000, v0
	v_and_b32_e32 v15, 0xffff0000, v1
	v_cndmask_b32_e32 v17, 0, v14, vcc
	v_lshlrev_b32_e32 v1, 16, v1
	v_mov_b32_e32 v16, v0
	v_mov_b32_e32 v14, v1
	v_pk_mul_f32 v[16:17], v[4:5], v[16:17]
	s_waitcnt vmcnt(1)
	v_lshlrev_b32_e32 v21, 16, v42
	v_pk_fma_f32 v[12:13], v[4:5], v[12:13], v[16:17] op_sel:[0,0,1] op_sel_hi:[1,0,0]
	v_pk_mul_f32 v[16:17], v[4:5], v[14:15] op_sel_hi:[0,1]
	v_mov_b32_e32 v20, v15
	v_pk_fma_f32 v[12:13], v[6:7], v[0:1], v[12:13] op_sel_hi:[0,1,1]
	v_pk_fma_f32 v[0:1], v[10:11], v[0:1], v[16:17] op_sel_hi:[0,1,1]
	v_pk_fma_f32 v[0:1], v[6:7], v[20:21], v[0:1] op_sel_hi:[0,1,1]
	v_pk_add_f32 v[16:17], v[8:9], v[0:1] op_sel_hi:[0,1]
	v_add_u32_e32 v0, 8, v22
	v_and_b32_e32 v0, s33, v0
	v_and_b32_e32 v1, 0xffff0000, v3
	s_waitcnt vmcnt(0)
; #define LAS __attribute__((address_space(3)))
; #define GAS __attribute__((address_space(1)))
; __device__ __forceinline__ void conv_item(const Params& P, int slice, int item, LAS unsigned char* lds) {
;     ...
;       for (int i4 = 0; i4 < 4; ++i4) {
;         const int tok = 8 * (ht + 256 * (4 * hh + i4));
;         const f32x4 a = sc4_apply(zr[i4][0], tok, L, w0, w1, w2, bb), bq = sc4_apply(zr[i4][1], tok + 4, L, w0, w1, w2, bb);
;         const int Bk = tok >> 7, bs = Bk / nblk;
;         u32x4 o; o.x = pk2(a[0], a[1]); o.y = pk2(a[2], a[3]); o.z = pk2(bq[0], bq[1]); o.w = pk2(bq[2], bq[3]);
;         *(LAS u32x4*)(Zs + Bk * ZBLK + bs * 32 + 2 * (tok & 127)) = o;
;       }
;       __builtin_amdgcn_sched_barrier(0);
;     }
;   }
;   const int nsteps = 2 * nblk - 1, dmin = -(nblk - 1);
;   const int aroA = (l16 & 7) * WIN_COPY + 2 * (128 + 8 * kc - 64 * wm - (l16 & 8));
;   const int wdo = (ht >> 5) * WIN_COPY + 4 * (ht & 31);
;   for (int order = 0; order < 2; ++order) {
;     const GAS u16* G = (const GAS u16*)(ws + (L == 2048 ? O_G2K : O_G16K)) + (size_t)(order * 1024 + c) * (size_t)(2 * L);
;     f32x4 acc[4][4];
; #pragma unroll
;     for (int a = 0; a < 4; ++a)
; #pragma unroll
;       for (int b2 = 0; b2 < 4; ++b2) acc[a][b2] = (f32x4){0.f, 0.f, 0.f, 0.f};
;     unsigned wl[8];
;     const int ub = L - 129 + 2 * (ht & 31) - (ht >> 5);
;     ...
;     { unsigned w4[CONV_GRP][8];
; #pragma unroll
;       for (int t0 = 0; t0 < CONV_GRP; ++t0) { CONV_LOADWIN(dmin + t0);
; #pragma unroll
;         for (int q = 0; q < 8; ++q) w4[t0][q] = wl[q]; }
;       __builtin_amdgcn_sched_barrier(0);
; #pragma unroll
;       for (int t0 = 0; t0 < CONV_GRP; ++t0) {
; #pragma unroll
;         for (int q = 0; q < 8; ++q) wl[q] = w4[t0][q];
;         CONV_STOREWIN(t0); }
;     }
;     __syncthreads();
;     const int q0 = 2 * wn, q1 = 2 * wn + 1;
;     const int lo0 = ((32 * q0) >> nbsh) - (nblk - 1), hi0 = (32 * q0 + 31) >> nbsh, lo1 = ((32 * q1) >> nbsh) - (nblk - 1), hi1 = (32 * q1 + 31) >> nbsh;
;     const int n0 = 32 * q0 + l16, n1 = 32 * q1 + l16;
;     const int bk0 = n0 >> nbsh, bs0 = n0 & (nb - 1); (void)n1;
;     const LAS unsigned char* zb0 = Zs + (bs0 * nblk) * ZBLK + bs0 * 32 + 16 * kc;
	v_lshlrev_b32_e32 v5, 16, v46
	v_cmp_ne_u32_e32 vcc, 0, v0
	v_and_b32_e32 v21, 16, v3
	v_and_b32_e32 v20, 0xffff0000, v2
	v_lshlrev_b32_e32 v23, 16, v3
	v_lshlrev_b32_e32 v3, 16, v2
	v_mov_b32_e32 v2, v15
	v_cndmask_b32_e32 v5, 0, v5, vcc
	v_pk_mov_b32 v[14:15], v[2:3], v[20:21] op_sel:[1,0]
	v_mov_b32_e32 v0, v23
	v_pk_mul_f32 v[14:15], v[4:5], v[14:15] op_sel_hi:[0,1]
	v_mov_b32_e32 v22, v20
	v_pk_fma_f32 v[2:3], v[10:11], v[2:3], v[14:15] op_sel_hi:[0,1,1]
	v_pk_mul_f32 v[14:15], v[4:5], v[0:1] op_sel_hi:[0,1]
	v_pk_fma_f32 v[14:15], v[10:11], v[22:23], v[14:15] op_sel_hi:[0,1,1]
	v_mov_b32_e32 v4, v1
	v_pk_fma_f32 v[2:3], v[6:7], v[22:23], v[2:3] op_sel_hi:[0,1,1]
	v_pk_fma_f32 v[0:1], v[6:7], v[4:5], v[14:15] op_sel_hi:[0,1,1]
	v_lshrrev_b32_e32 v6, 4, v19
	v_pk_add_f32 v[12:13], v[8:9], v[12:13] op_sel_hi:[0,1]
	v_pk_add_f32 v[2:3], v[8:9], v[2:3] op_sel_hi:[0,1]
	v_pk_add_f32 v[4:5], v[8:9], v[0:1] op_sel_hi:[0,1]
	v_lshrrev_b32_e32 v8, s86, v6
	v_cvt_pk_bf16_f32 v2, v2, v3
	v_cvt_pk_bf16_f32 v3, v4, v5
	v_mad_u32_u24 v4, v6, s85, v18
	v_lshlrev_b32_e32 v5, 5, v8
	v_cvt_pk_bf16_f32 v0, v12, v13
	v_cvt_pk_bf16_f32 v1, v16, v17
	v_add3_u32 v4, v4, v5, v11
	ds_write_b128 v4, v[0:3]
	v_readlane_b32 s4, v254, 14
	v_and_b32_e32 v4, 31, v9
	s_add_u32 s13, s0, s4
	v_lshlrev_b32_e32 v5, 2, v4
	s_addc_u32 s22, s1, 0
	v_lshlrev_b32_e32 v4, 1, v4
	v_readlane_b32 s4, v254, 15
	s_lshl_b32 s23, s8, 6
	v_bfe_u32 v2, v9, 5, 3
	v_add_u32_e32 v6, s4, v4
	s_or_b32 s4, s23, 31
	s_ashr_i32 s26, s4, s94
	s_or_b32 s4, s23, 32
	s_ashr_i32 s4, s4, s94
	v_and_or_b32 v1, v9, 8, s18
	v_mul_u32_u24_e32 v3, 0x240, v2
	s_ashr_i32 s24, s23, s94
	s_sub_i32 s27, s4, s88
	s_or_b32 s4, s23, 63
	v_and_b32_e32 v0, 7, v9
	v_lshlrev_b32_e32 v1, 1, v1
	v_add3_u32 v157, s3, v3, v5
	s_sub_i32 s25, s24, s88
	s_ashr_i32 s28, s4, s94
	v_and_or_b32 v3, v9, 15, s23
	v_mul_u32_u24_e32 v0, 0x240, v0
	v_sub_u32_e32 v1, v7, v1
	v_ashrrev_i32_e32 v242, s94, v3
	v_and_b32_e32 v3, s56, v9
	s_cmp_lt_i32 s89, s25
	v_lshlrev_b32_e32 v5, s86, v3
	s_cselect_b64 s[4:5], -1, 0
	v_add3_u32 v243, s3, v1, v0
	v_readlane_b32 s3, v254, 30
	s_sub_i32 s64, s26, s30
	s_sub_i32 s92, s28, s30
	v_mad_u32_u24 v8, v5, s85, v18
	v_lshlrev_b32_e32 v3, 5, v3
	s_add_i32 s29, 0, 0x23400
	s_add_i32 s34, s25, s30
	s_add_i32 s35, s27, s30
	v_add_u32_e32 v247, s3, v242
	s_add_i32 s3, s64, 1
	s_add_i32 s84, s26, 1
	s_add_i32 s93, s92, 1
	s_add_i32 s99, s28, 1
	v_sub_u32_e32 v6, v6, v2
	v_add3_u32 v156, v8, v3, v7
	v_readlane_b32 s8, v254, 23
	v_subrev_u32_e32 v9, s25, v242
	v_add_u32_e32 v245, s30, v242
	s_add_u32 s0, s0, s6
	v_add_u32_e32 v8, s8, v6
	v_mad_u64_u32 v[0:1], s[8:9], v9, s85, v[156:157]
	v_mov_b32_e32 v10, s29
	v_cmp_gt_u32_e32 vcc, s61, v9
	v_subrev_u32_e32 v9, s25, v245
	s_addc_u32 s1, s1, s7
	v_cndmask_b32_e32 v244, v10, v0, vcc
	v_mad_u64_u32 v[0:1], s[8:9], v9, s85, v[156:157]
	v_cmp_gt_u32_e32 vcc, s61, v9
	s_add_u32 s14, s0, 0x31912000
	v_readlane_b32 s0, v254, 16
	v_cndmask_b32_e32 v246, v10, v0, vcc
	s_addc_u32 s15, s1, 0
	v_add_u32_e32 v0, s0, v6
	v_mov_b32_e32 v1, s0
	v_cmp_le_u32_e32 vcc, s60, v0
	v_add_u32_e32 v248, s30, v247
	v_mov_b32_e32 v159, v81
	v_addc_co_u32_e32 v9, vcc, v6, v1, vcc
	v_cmp_le_u32_e32 vcc, s33, v0
	v_min_u32_e32 v158, s95, v9
	v_add_u32_e32 v9, 64, v0
	v_addc_co_u32_e64 v10, s[0:1], v6, v1, vcc
	v_add_u32_e32 v10, 1, v10
	v_cmp_le_u32_e64 s[0:1], s60, v9
	v_min_u32_e32 v160, s95, v10
	v_mov_b32_e32 v161, v81
	v_addc_co_u32_e64 v10, s[0:1], 64, v0, s[0:1]
	v_cmp_le_u32_e64 s[0:1], s33, v9
	v_min_u32_e32 v162, s95, v10
	v_mov_b32_e32 v163, v81
	v_addc_co_u32_e64 v9, s[6:7], v6, v1, s[0:1]
	v_add_u32_e32 v9, 0x41, v9
	v_min_u32_e32 v164, s95, v9
	v_add_u32_e32 v9, 0x80, v0
	v_cmp_le_u32_e64 s[6:7], s60, v9
	v_mov_b32_e32 v165, v81
	v_mov_b32_e32 v167, v81
	v_addc_co_u32_e64 v10, s[6:7], v0, v230, s[6:7]
	v_cmp_le_u32_e64 s[6:7], s33, v9
	v_min_u32_e32 v166, s95, v10
	v_mov_b32_e32 v169, v81
	v_addc_co_u32_e64 v9, s[6:7], v6, v1, s[6:7]
	v_add_u32_e32 v9, 0x81, v9
	v_min_u32_e32 v168, s95, v9
	v_add_u32_e32 v9, 0xc0, v0
	v_cmp_le_u32_e64 s[6:7], s60, v9
	v_mov_b32_e32 v171, v81
	v_mov_b32_e32 v173, v81
	v_addc_co_u32_e64 v10, s[6:7], v0, v231, s[6:7]
; #define LAS __attribute__((address_space(3)))
; #define GAS __attribute__((address_space(1)))
; #define CONV_STOREWIN(t) do { LAS unsigned char* wd_ = Wn + ((((t) >> 2) & 1) * CONV_GRP + ((t) & 3)) * WIN_BYTES + wdo; _Pragma("unroll") for (int q = 0; q < 8; ++q) LAUNDER_V(wl[q]); _Pragma("unroll") for (int q = 0; q < 4; ++q) \
;       *(LAS unsigned*)(wd_ + 128 * q) = wl[2 * q] | (wl[2 * q + 1] << 16); } while (0)
; __device__ __forceinline__ void conv_item(const Params& P, int slice, int item, LAS unsigned char* lds) {
;     ...
;   const int nsteps = 2 * nblk - 1, dmin = -(nblk - 1);
;   const int aroA = (l16 & 7) * WIN_COPY + 2 * (128 + 8 * kc - 64 * wm - (l16 & 8));
;   const int wdo = (ht >> 5) * WIN_COPY + 4 * (ht & 31);
;   for (int order = 0; order < 2; ++order) {
;     const GAS u16* G = (const GAS u16*)(ws + (L == 2048 ? O_G2K : O_G16K)) + (size_t)(order * 1024 + c) * (size_t)(2 * L);
;     f32x4 acc[4][4];
; #pragma unroll
;     for (int a = 0; a < 4; ++a)
; #pragma unroll
;       for (int b2 = 0; b2 < 4; ++b2) acc[a][b2] = (f32x4){0.f, 0.f, 0.f, 0.f};
;     unsigned wl[8];
;     const int ub = L - 129 + 2 * (ht & 31) - (ht >> 5);
;     ...
;     { unsigned w4[CONV_GRP][8];
; #pragma unroll
;       for (int t0 = 0; t0 < CONV_GRP; ++t0) { CONV_LOADWIN(dmin + t0);
; #pragma unroll
;         for (int q = 0; q < 8; ++q) w4[t0][q] = wl[q]; }
;       __builtin_amdgcn_sched_barrier(0);
; #pragma unroll
;       for (int t0 = 0; t0 < CONV_GRP; ++t0) {
; #pragma unroll
;         for (int q = 0; q < 8; ++q) wl[q] = w4[t0][q];
;         CONV_STOREWIN(t0); }
;     }
;     __syncthreads();
;     const int q0 = 2 * wn, q1 = 2 * wn + 1;
;     const int lo0 = ((32 * q0) >> nbsh) - (nblk - 1), hi0 = (32 * q0 + 31) >> nbsh, lo1 = ((32 * q1) >> nbsh) - (nblk - 1), hi1 = (32 * q1 + 31) >> nbsh;
;     const int n0 = 32 * q0 + l16, n1 = 32 * q1 + l16;
;     const int bk0 = n0 >> nbsh, bs0 = n0 & (nb - 1); (void)n1;
;     const LAS unsigned char* zb0 = Zs + (bs0 * nblk) * ZBLK + bs0 * 32 + 16 * kc;
	v_cmp_le_u32_e64 s[6:7], s33, v9
	v_mov_b32_e32 v9, 0xffffff80
	v_min_u32_e32 v170, s95, v10
	v_addc_co_u32_e64 v1, s[6:7], v6, v1, s[6:7]
	v_add_u32_e32 v1, 0xc1, v1
	v_min_u32_e32 v172, s95, v1
	v_add_u32_e32 v1, 0xffffff80, v0
	v_cmp_le_u32_e64 s[6:7], s60, v1
	v_mov_b32_e32 v175, v81
	v_mov_b32_e32 v177, v81
	v_addc_co_u32_e64 v6, s[6:7], v0, v9, s[6:7]
	v_cmp_le_u32_e64 s[6:7], s33, v1
	v_min_u32_e32 v174, s95, v6
	v_mov_b32_e32 v181, v81
	v_addc_co_u32_e64 v1, s[8:9], v0, v9, s[6:7]
	v_add_u32_e32 v1, 1, v1
	v_min_u32_e32 v176, s95, v1
	v_subrev_u32_e32 v1, 64, v0
	v_cmp_le_u32_e64 s[8:9], s33, v1
	v_mov_b32_e32 v179, v81
	v_mov_b32_e32 v183, v81
	v_addc_co_u32_e64 v6, s[10:11], v0, v9, s[8:9]
	v_cmp_le_u32_e64 s[10:11], s60, v1
	v_not_b32_e32 v1, 63
	v_add_u32_e32 v6, 0x41, v6
	v_addc_co_u32_e64 v1, s[10:11], v0, v1, s[10:11]
	v_min_u32_e32 v180, s95, v1
	v_addc_co_u32_e32 v1, vcc, v0, v9, vcc
	v_add_u32_e32 v1, 0x81, v1
	v_min_u32_e32 v182, s95, v1
	v_addc_co_u32_e64 v1, vcc, v0, v9, s[0:1]
	v_add_u32_e32 v1, 0xc1, v1
	v_min_u32_e32 v184, s95, v1
	v_add_u32_e32 v1, 0xffffff00, v0
	v_cmp_le_u32_e32 vcc, s60, v1
	v_mov_b32_e32 v9, 0xffffff00
	v_min_u32_e32 v178, s95, v6
	v_addc_co_u32_e32 v6, vcc, v0, v9, vcc
	v_cmp_le_u32_e32 vcc, s33, v1
	v_min_u32_e32 v186, s95, v6
	v_mov_b32_e32 v6, 0xffffff40
	v_addc_co_u32_e32 v1, vcc, v0, v9, vcc
	v_add_u32_e32 v1, 1, v1
	v_min_u32_e32 v188, s95, v1
	v_add_u32_e32 v1, 0xffffff40, v0
	v_cmp_le_u32_e32 vcc, s60, v1
	v_readlane_b32 s0, v254, 25
	v_readlane_b32 s1, v254, 28
	v_addc_co_u32_e32 v6, vcc, v0, v6, vcc
	v_cmp_le_u32_e32 vcc, s33, v1
	v_add_u32_e32 v235, s1, v242
	v_readlane_b32 s1, v254, 32
	v_addc_co_u32_e32 v1, vcc, v0, v9, vcc
	v_add_u32_e32 v1, 0x41, v1
	v_min_u32_e32 v192, s95, v1
	v_addc_co_u32_e64 v1, vcc, v0, v9, s[6:7]
	v_addc_co_u32_e64 v0, vcc, v0, v9, s[8:9]
	v_add_u32_e32 v0, 0xc1, v0
	v_min_u32_e32 v196, s95, v0
	v_add_u32_e32 v0, 0xfffffe00, v8
	v_add_u32_e32 v1, 0x81, v1
	v_cmp_le_u32_e32 vcc, s60, v0
	v_min_u32_e32 v194, s95, v1
	v_mov_b32_e32 v185, v81
	v_addc_co_u32_e32 v1, vcc, v8, v234, vcc
	v_cmp_le_u32_e32 vcc, s33, v0
	v_min_u32_e32 v198, s95, v1
	v_mov_b32_e32 v1, 0xfffffe40
	v_addc_co_u32_e32 v0, vcc, v8, v234, vcc
	v_add_u32_e32 v0, 1, v0
	v_min_u32_e32 v200, s95, v0
	v_add_u32_e32 v0, 0xfffffe40, v8
	v_cmp_le_u32_e32 vcc, s60, v0
	v_mov_b32_e32 v187, v81
	v_mov_b32_e32 v189, v81
	v_addc_co_u32_e32 v1, vcc, v8, v1, vcc
	v_cmp_le_u32_e32 vcc, s33, v0
	v_min_u32_e32 v202, s95, v1
	v_mov_b32_e32 v1, 0xfffffe80
	v_addc_co_u32_e32 v0, vcc, v8, v234, vcc
	v_add_u32_e32 v0, 0x41, v0
	v_min_u32_e32 v204, s95, v0
	v_add_u32_e32 v0, 0xfffffe80, v8
	v_cmp_le_u32_e32 vcc, s60, v0
	v_min_u32_e32 v190, s95, v6
	v_mov_b32_e32 v191, v81
	v_addc_co_u32_e32 v1, vcc, v8, v1, vcc
	v_cmp_le_u32_e32 vcc, s33, v0
	v_min_u32_e32 v206, s95, v1
	v_mov_b32_e32 v1, 0xfffffec0
	v_addc_co_u32_e32 v0, vcc, v8, v234, vcc
	v_add_u32_e32 v0, 0x81, v0
	v_min_u32_e32 v208, s95, v0
	v_add_u32_e32 v0, 0xfffffec0, v8
	v_cmp_le_u32_e32 vcc, s60, v0
	v_mov_b32_e32 v193, v81
	v_mov_b32_e32 v195, v81
	v_addc_co_u32_e32 v1, vcc, v8, v1, vcc
	v_cmp_le_u32_e32 vcc, s33, v0
	v_min_u32_e32 v210, s95, v1
	v_mul_lo_u32 v1, v245, s85
	v_addc_co_u32_e32 v0, vcc, v8, v234, vcc
	v_add_u32_e32 v0, 0xc1, v0
	v_min_u32_e32 v212, s95, v0
	v_add_u32_e32 v0, s0, v4
	v_readlane_b32 s0, v254, 26
	v_sub_u32_e32 v249, v0, v2
	v_mov_b32_e32 v197, v81
	v_add_u32_e32 v0, s0, v4
	v_sub_u32_e32 v250, v0, v2
	v_mov_b32_e32 v0, s16
	v_mad_u32_u24 v0, v5, s85, v0
	v_add3_u32 v0, v0, v3, v7
	v_readlane_b32 s0, v253, 46
	v_mov_b32_e32 v199, v81
	v_mov_b32_e32 v201, v81
	v_add3_u32 v252, v0, v1, s0
	v_mul_lo_u32 v1, v242, s85
	v_add3_u32 v241, v0, v1, s0
	v_mul_lo_u32 v1, v248, s85
	v_add3_u32 v237, v0, v1, s0
	v_mul_lo_u32 v1, v247, s85
	v_add3_u32 v224, v0, v1, s0
	v_readlane_b32 s0, v254, 34
	v_mov_b32_e32 v203, v81
	v_mov_b32_e32 v205, v81
	v_mov_b32_e32 v207, v81
	v_mov_b32_e32 v209, v81
	v_mov_b32_e32 v211, v81
	v_mov_b32_e32 v213, v81
	v_add_u32_e32 v251, -1, v242
	v_add_u32_e32 v214, 0, v0
	v_add_u32_e32 v236, s1, v242
	v_add_u32_e32 v232, s0, v242
	s_mov_b64 s[0:1], -1
	s_branch .LBB0_387

; #define CONV_STOREWIN(t) do { LAS unsigned char* wd_ = Wn + ((((t) >> 2) & 1) * CONV_GRP + ((t) & 3)) * WIN_BYTES + wdo; _Pragma("unroll") for (int q = 0; q < 8; ++q) LAUNDER_V(wl[q]); _Pragma("unroll") for (int q = 0; q < 4; ++q) \
;       *(LAS unsigned*)(wd_ + 128 * q) = wl[2 * q] | (wl[2 * q + 1] << 16); } while (0)
; __device__ __forceinline__ void conv_item(const Params& P, int slice, int item, LAS unsigned char* lds) {
;     ...
;     { unsigned w4[CONV_GRP][8];
; #pragma unroll
;       for (int t0 = 0; t0 < CONV_GRP; ++t0) { CONV_LOADWIN(dmin + t0);
; #pragma unroll
;         for (int q = 0; q < 8; ++q) w4[t0][q] = wl[q]; }
;       __builtin_amdgcn_sched_barrier(0);
; #pragma unroll
;       for (int t0 = 0; t0 < CONV_GRP; ++t0) {
; #pragma unroll
;         for (int q = 0; q < 8; ++q) wl[q] = w4[t0][q];
;         CONV_STOREWIN(t0); }
;     }
.LBB0_387:
	s_add_i32 s6, s17, s12
	s_ashr_i32 s7, s6, 31
	s_lshl_b64 s[8:9], s[6:7], s98
	s_lshl_b64 s[8:9], s[8:9], 1
	s_add_u32 s8, s13, s8
	s_addc_u32 s9, s22, s9
	v_lshl_add_u32 v0, v249, 1, v227
	global_load_dword v10, v0, s[8:9] offset:-1024
	global_load_dword v11, v0, s[8:9] offset:-896
	global_load_dword v12, v0, s[8:9] offset:-768
	global_load_dword v13, v0, s[8:9] offset:-640
	global_load_dword v14, v0, s[8:9] offset:-1280
	global_load_dword v15, v0, s[8:9] offset:-1152
	global_load_dword v16, v0, s[8:9] offset:-1024
	global_load_dword v17, v0, s[8:9] offset:-896
	global_load_dword v18, v0, s[8:9] offset:-1536
	global_load_dword v19, v0, s[8:9] offset:-1408
	global_load_dword v20, v0, s[8:9] offset:-1280
	global_load_dword v21, v0, s[8:9] offset:-1152
	global_load_dword v22, v0, s[8:9] offset:-1792
	global_load_dword v23, v0, s[8:9] offset:-1664
	global_load_dword v24, v0, s[8:9] offset:-1536
	global_load_dword v25, v0, s[8:9] offset:-1408
	v_add_u32_e32 v1, 0x1200, v157
	v_add_u32_e32 v2, 0x2400, v157
	v_add_u32_e32 v3, 0x3600, v157
	s_waitcnt vmcnt(12)
	ds_write2_b32 v157, v10, v11 offset1:32
	ds_write2_b32 v157, v12, v13 offset0:64 offset1:96
	s_waitcnt vmcnt(8)
	ds_write2_b32 v1, v14, v15 offset1:32
	ds_write2_b32 v1, v16, v17 offset0:64 offset1:96
	s_waitcnt vmcnt(4)
	ds_write2_b32 v2, v18, v19 offset1:32
	ds_write2_b32 v2, v20, v21 offset0:64 offset1:96
	s_waitcnt vmcnt(0)
	ds_write2_b32 v3, v22, v23 offset1:32
	s_andn2_b64 vcc, exec, s[4:5]
	ds_write2_b32 v3, v24, v25 offset0:64 offset1:96
	s_waitcnt lgkmcnt(0)
	s_barrier
	s_cbranch_vccnz .LBB0_396
	s_mov_b32 s16, 0
	v_mov_b32_e32 v8, v249
	s_branch .LBB0_390

; #define CONV_HEAD() const int step = d - dmin; if (step + CONV_GRP < nsteps) CONV_LOADWIN(d + CONV_GRP); __builtin_amdgcn_sched_barrier(0)
; #define CONV_TAIL() if (step + CONV_GRP < nsteps) CONV_STOREWIN(step + CONV_GRP); if ((step & 1) == 1 || step + 1 == nsteps) __syncthreads()
; __device__ __forceinline__ void conv_item(const Params& P, int slice, int item, LAS unsigned char* lds) {
;     ...
;     for (int d = dmin; d < lo0; ++d) { CONV_HEAD(); CONV_TAIL(); }
.LBB0_392:
	s_andn2_b64 vcc, exec, s[10:11]
	s_cbranch_vccnz .LBB0_394
	s_and_b32 s10, s17, 4
	s_and_b32 s11, s16, 3
	s_or_b32 s10, s10, s11
	s_mulk_i32 s10, 0x1200
	v_add_u32_e32 v9, s10, v157
	s_waitcnt vmcnt(0)
	ds_write2_b32 v9, v230, v231 offset1:32
	ds_write2_b32 v9, v238, v239 offset0:64 offset1:96

; #define LAS __attribute__((address_space(3)))
; #define CONV_HEAD() const int step = d - dmin; if (step + CONV_GRP < nsteps) CONV_LOADWIN(d + CONV_GRP); __builtin_amdgcn_sched_barrier(0)
; #define CONV_TAIL() if (step + CONV_GRP < nsteps) CONV_STOREWIN(step + CONV_GRP); if ((step & 1) == 1 || step + 1 == nsteps) __syncthreads()
; #define CONV_DS(x) ({ int t_ = (x); LAUNDER_S(t_); t_; })
; __device__ __forceinline__ void conv_item(const Params& P, int slice, int item, LAS unsigned char* lds) {
;     ...
;     for (int d = dmin; d < lo0; ++d) { CONV_HEAD(); CONV_TAIL(); }
;     {
;       const LAS unsigned char* wb = CONV_WB(lo0 - dmin); const LAS unsigned char* bp0 = CONV_BPH(0, 0, lo0); const LAS unsigned char* bp1 = CONV_BPH(0, 1, lo0);
; #pragma unroll
;       for (int k = 0; k < 10; ++k) fa[k] = *(const LAS bf16x8*)(wb + 32 * (k - 3));
; #pragma unroll
;       for (int ks = 0; ks < 4; ++ks) { fb[ks] = *(const LAS bf16x8*)(bp0 + 64 * ks); fb[4 + ks] = *(const LAS bf16x8*)(bp1 + 64 * ks); }
;     }
;     const int hw = 16 >> nbsh;
;     ...
;     for (int d = CONV_DS(lo0); d < lo0 + hw; ++d) { CONV_HEADT(); CONV_TILESTEP(0, CONV_BPH(0, 0, d + 1), CONV_BPH(0, 1, d + 1), 1, CONV_WB(step + 1), 1, 1); CONV_TAIL(); }
.LBB0_399:
	s_add_i32 s68, s61, s16
	s_add_i32 s17, s68, -1
	s_setprio 1
	v_lshl_add_u32 v240, v40, 1, v227
	global_load_dword v230, v240, s[8:9] offset:-2048
	global_load_dword v231, v240, s[8:9] offset:-1920
	global_load_dword v238, v240, s[8:9] offset:-1792
	global_load_dword v239, v240, s[8:9] offset:-1664
	v_add_u32_e32 v44, s30, v41
	s_and_b32 s0, s68, 7
	s_mulk_i32 s0, 0x1200
	s_waitcnt lgkmcnt(1)
	v_mfma_f32_16x16x32_bf16 v[12:15], v[88:91], v[144:147], v[12:15]
	v_mfma_f32_16x16x32_bf16 v[4:7], v[72:75], v[144:147], v[16:19]
	v_mfma_f32_16x16x32_bf16 v[16:19], v[64:67], v[144:147], v[20:23]
	v_mfma_f32_16x16x32_bf16 v[8:11], v[76:79], v[144:147], v[8:11]
	v_add_u32_e32 v51, s0, v243
	s_waitcnt lgkmcnt(6)
	v_mfma_f32_16x16x32_bf16 v[12:15], v[72:75], v[140:143], v[12:15]
	ds_read_b128 v[72:75], v51 offset:256
	v_mov_b32_e32 v45, s29
	v_cmp_gt_u32_e32 vcc, s61, v41
	v_cmp_gt_u32_e64 s[0:1], s61, v44
	s_nop 0
	v_cndmask_b32_e32 v50, v45, v43, vcc
	s_nop 0
	v_cndmask_b32_e64 v52, v45, v42, s[0:1]
	v_mfma_f32_16x16x32_bf16 v[4:7], v[56:59], v[140:143], v[4:7]
	v_mfma_f32_16x16x32_bf16 v[16:19], v[60:63], v[140:143], v[16:19]
	s_waitcnt lgkmcnt(4)
	v_mfma_f32_16x16x32_bf16 v[4:7], v[28:31], v[136:139], v[4:7]
	ds_read_b128 v[76:79], v51 offset:160
	ds_read_b128 v[88:91], v51 offset:192
	s_waitcnt lgkmcnt(3)
	ds_read_b128 v[116:119], v52 offset:192
	v_mfma_f32_16x16x32_bf16 v[20:23], v[24:27], v[136:139], v[16:19]
	s_nop 2
	v_mfma_f32_16x16x32_bf16 v[16:19], v[32:35], v[132:135], v[4:7]
	v_mfma_f32_16x16x32_bf16 v[8:11], v[64:67], v[140:143], v[8:11]
	v_mfma_f32_16x16x32_bf16 v[12:15], v[56:59], v[136:139], v[12:15]
	v_mfma_f32_16x16x32_bf16 v[8:11], v[60:63], v[136:139], v[8:11]
	ds_read_b128 v[136:139], v50 offset:128
	v_mfma_f32_16x16x32_bf16 v[12:15], v[28:31], v[132:135], v[12:15]
	v_mfma_f32_16x16x32_bf16 v[20:23], v[36:39], v[132:135], v[20:23]
	v_mfma_f32_16x16x32_bf16 v[8:11], v[24:27], v[132:135], v[8:11]
	ds_read_b128 v[32:35], v51 offset:448
	ds_read_b128 v[28:31], v51 offset:384
	ds_read_b128 v[36:39], v51 offset:416
	ds_read_b128 v[24:27], v51 offset:352
	ds_read_b128 v[60:63], v51 offset:288
	ds_read_b128 v[56:59], v51 offset:320
	ds_read_b128 v[132:135], v50 offset:192
	ds_read_b128 v[120:123], v52 offset:128
	ds_read_b128 v[140:143], v50 offset:64
	ds_read_b128 v[124:127], v52 offset:64
	ds_read_b128 v[64:67], v51 offset:224
	ds_read_b128 v[144:147], v50
	ds_read_b128 v[128:131], v52
	s_setprio 0
	s_add_i32 s68, s68, 3
	s_cmp_ge_i32 s68, s87
	s_cbranch_scc1 .LBB0_401
	s_and_b32 s0, s68, 4
	s_and_b32 s1, s17, 3
	s_or_b32 s0, s0, s1
	s_mulk_i32 s0, 0x1200
	v_add_u32_e32 v44, s0, v157
	s_waitcnt vmcnt(0)
	ds_write2_b32 v44, v230, v231 offset1:32
	ds_write2_b32 v44, v238, v239 offset0:64 offset1:96

; #define LAS __attribute__((address_space(3)))
; #define CONV_HEAD() const int step = d - dmin; if (step + CONV_GRP < nsteps) CONV_LOADWIN(d + CONV_GRP); __builtin_amdgcn_sched_barrier(0)
; #define CONV_TAIL() if (step + CONV_GRP < nsteps) CONV_STOREWIN(step + CONV_GRP); if ((step & 1) == 1 || step + 1 == nsteps) __syncthreads()
; #define CONV_DS(x) ({ int t_ = (x); LAUNDER_S(t_); t_; })
; __device__ __forceinline__ void conv_item(const Params& P, int slice, int item, LAS unsigned char* lds) {
;     ...
;     for (int d = dmin; d < lo0; ++d) { CONV_HEAD(); CONV_TAIL(); }
;     {
;       const LAS unsigned char* wb = CONV_WB(lo0 - dmin); const LAS unsigned char* bp0 = CONV_BPH(0, 0, lo0); const LAS unsigned char* bp1 = CONV_BPH(0, 1, lo0);
; #pragma unroll
;       for (int k = 0; k < 10; ++k) fa[k] = *(const LAS bf16x8*)(wb + 32 * (k - 3));
; #pragma unroll
;       for (int ks = 0; ks < 4; ++ks) { fb[ks] = *(const LAS bf16x8*)(bp0 + 64 * ks); fb[4 + ks] = *(const LAS bf16x8*)(bp1 + 64 * ks); }
;     }
;     const int hw = 16 >> nbsh;
;     ...
;     for (int d = CONV_DS(lo0); d < lo0 + hw; ++d) { CONV_HEADT(); CONV_TILESTEP(0, CONV_BPH(0, 0, d + 1), CONV_BPH(0, 1, d + 1), 1, CONV_WB(step + 1), 1, 1); CONV_TAIL(); }
;     for (int d = CONV_DS(lo0 + hw); d < lo1; ++d) { CONV_HEADT(); CONV_TILESTEP(0, CONV_BPH(0, 0, d + 1), CONV_BPH(0, 1, d + 1), 1, CONV_WB(step + 1), 3, 1); CONV_TAIL(); }
.LBB0_407:
	s_add_i32 s68, s61, s16
	s_add_i32 s17, s68, -1
	s_setprio 1
	v_lshl_add_u32 v240, v68, 1, v227
	global_load_dword v230, v240, s[8:9] offset:-2048
	global_load_dword v231, v240, s[8:9] offset:-1920
	global_load_dword v238, v240, s[8:9] offset:-1792
	global_load_dword v239, v240, s[8:9] offset:-1664
	v_add_u32_e32 v86, s30, v69
	s_and_b32 s0, s68, 7
	s_mulk_i32 s0, 0x1200
	s_waitcnt lgkmcnt(1)
	v_mfma_f32_16x16x32_bf16 v[0:3], v[72:75], v[144:147], v[16:19]
	v_mfma_f32_16x16x32_bf16 v[4:7], v[64:67], v[144:147], v[20:23]
	v_mfma_f32_16x16x32_bf16 v[12:15], v[88:91], v[144:147], v[12:15]
	v_mfma_f32_16x16x32_bf16 v[8:11], v[76:79], v[144:147], v[8:11]
	s_waitcnt lgkmcnt(0)
	v_mfma_f32_16x16x32_bf16 v[16:19], v[72:75], v[128:131], v[52:55]
	v_mfma_f32_16x16x32_bf16 v[0:3], v[56:59], v[140:143], v[0:3]
	v_mfma_f32_16x16x32_bf16 v[16:19], v[56:59], v[124:127], v[16:19]
	v_mfma_f32_16x16x32_bf16 v[0:3], v[28:31], v[136:139], v[0:3]
	v_mfma_f32_16x16x32_bf16 v[20:23], v[28:31], v[120:123], v[16:19]
	v_mfma_f32_16x16x32_bf16 v[16:19], v[32:35], v[132:135], v[0:3]
	v_mfma_f32_16x16x32_bf16 v[52:55], v[32:35], v[116:119], v[20:23]
	v_mfma_f32_16x16x32_bf16 v[20:23], v[64:67], v[128:131], v[48:51]
	s_nop 3
	v_mfma_f32_16x16x32_bf16 v[44:47], v[88:91], v[128:131], v[44:47]
	v_mfma_f32_16x16x32_bf16 v[12:15], v[72:75], v[140:143], v[12:15]
	v_mfma_f32_16x16x32_bf16 v[44:47], v[72:75], v[124:127], v[44:47]
	v_mfma_f32_16x16x32_bf16 v[40:43], v[76:79], v[128:131], v[40:43]
	v_mov_b32_e32 v72, s29
	v_mfma_f32_16x16x32_bf16 v[12:15], v[56:59], v[136:139], v[12:15]
	v_mfma_f32_16x16x32_bf16 v[44:47], v[56:59], v[120:123], v[44:47]
	v_mfma_f32_16x16x32_bf16 v[2:5], v[60:63], v[140:143], v[4:7]
	v_mfma_f32_16x16x32_bf16 v[20:23], v[60:63], v[124:127], v[20:23]
	v_mfma_f32_16x16x32_bf16 v[2:5], v[24:27], v[136:139], v[2:5]
	v_mfma_f32_16x16x32_bf16 v[48:51], v[24:27], v[120:123], v[20:23]
	v_mfma_f32_16x16x32_bf16 v[20:23], v[36:39], v[132:135], v[2:5]
	v_mfma_f32_16x16x32_bf16 v[2:5], v[64:67], v[140:143], v[8:11]
	v_mfma_f32_16x16x32_bf16 v[6:9], v[64:67], v[124:127], v[40:43]
	v_mfma_f32_16x16x32_bf16 v[2:5], v[60:63], v[136:139], v[2:5]
	v_mfma_f32_16x16x32_bf16 v[40:43], v[60:63], v[120:123], v[6:9]
	v_mfma_f32_16x16x32_bf16 v[8:11], v[24:27], v[132:135], v[2:5]
	s_nop 5
	v_cmp_gt_u32_e32 vcc, s61, v69
	s_nop 0
	s_nop 0
	v_cndmask_b32_e32 v82, v72, v71, vcc
	ds_read_b128 v[136:139], v82 offset:128
	v_add_u32_e32 v87, s0, v243
	v_cmp_gt_u32_e64 s[0:1], s61, v86
	s_nop 1
	v_cndmask_b32_e64 v74, v72, v70, s[0:1]
	ds_read_b128 v[88:91], v87 offset:192
	ds_read_b128 v[124:127], v74 offset:64
	ds_read_b128 v[120:123], v74 offset:128
	ds_read_b128 v[128:131], v74
	v_mfma_f32_16x16x32_bf16 v[44:47], v[28:31], v[116:119], v[44:47]
	v_mfma_f32_16x16x32_bf16 v[48:51], v[36:39], v[116:119], v[48:51]
	v_mfma_f32_16x16x32_bf16 v[40:43], v[24:27], v[116:119], v[40:43]
	ds_read_b128 v[116:119], v74 offset:192
	ds_read_b128 v[72:75], v87 offset:256
	ds_read_b128 v[32:35], v87 offset:448
	ds_read_b128 v[76:79], v87 offset:160
	v_mfma_f32_16x16x32_bf16 v[12:15], v[28:31], v[132:135], v[12:15]
	ds_read_b128 v[28:31], v87 offset:384
	ds_read_b128 v[144:147], v82
	ds_read_b128 v[140:143], v82 offset:64
	ds_read_b128 v[64:67], v87 offset:224
	ds_read_b128 v[36:39], v87 offset:416
	ds_read_b128 v[24:27], v87 offset:352
	ds_read_b128 v[132:135], v82 offset:192
	ds_read_b128 v[60:63], v87 offset:288
	ds_read_b128 v[56:59], v87 offset:320
	s_setprio 0
	s_add_i32 s68, s68, 3
	s_cmp_ge_i32 s68, s87
	s_cbranch_scc1 .LBB0_409
	s_and_b32 s0, s68, 4
	s_and_b32 s1, s17, 3
	s_or_b32 s0, s0, s1
	s_mulk_i32 s0, 0x1200
	v_add_u32_e32 v80, s0, v157
	s_waitcnt vmcnt(0)
	ds_write2_b32 v80, v230, v231 offset1:32
	ds_write2_b32 v80, v238, v239 offset0:64 offset1:96

; #define LAS __attribute__((address_space(3)))
; #define CONV_HEAD() const int step = d - dmin; if (step + CONV_GRP < nsteps) CONV_LOADWIN(d + CONV_GRP); __builtin_amdgcn_sched_barrier(0)
; #define CONV_TAIL() if (step + CONV_GRP < nsteps) CONV_STOREWIN(step + CONV_GRP); if ((step & 1) == 1 || step + 1 == nsteps) __syncthreads()
; #define CONV_DS(x) ({ int t_ = (x); LAUNDER_S(t_); t_; })
; #define CONV_NB1(H) ((d + 1 <= hi0) ? CONV_BPH(0, H, d + 1) : CONV_BPH(1, H, d + 1))
; __device__ __forceinline__ void conv_item(const Params& P, int slice, int item, LAS unsigned char* lds) {
;     ...
;     for (int d = dmin; d < lo0; ++d) { CONV_HEAD(); CONV_TAIL(); }
;     {
;       const LAS unsigned char* wb = CONV_WB(lo0 - dmin); const LAS unsigned char* bp0 = CONV_BPH(0, 0, lo0); const LAS unsigned char* bp1 = CONV_BPH(0, 1, lo0);
; #pragma unroll
;       for (int k = 0; k < 10; ++k) fa[k] = *(const LAS bf16x8*)(wb + 32 * (k - 3));
; #pragma unroll
;       for (int ks = 0; ks < 4; ++ks) { fb[ks] = *(const LAS bf16x8*)(bp0 + 64 * ks); fb[4 + ks] = *(const LAS bf16x8*)(bp1 + 64 * ks); }
;     }
;     const int hw = 16 >> nbsh;
;     ...
;     for (int d = CONV_DS(lo0); d < lo0 + hw; ++d) { CONV_HEADT(); CONV_TILESTEP(0, CONV_BPH(0, 0, d + 1), CONV_BPH(0, 1, d + 1), 1, CONV_WB(step + 1), 1, 1); CONV_TAIL(); }
;     for (int d = CONV_DS(lo0 + hw); d < lo1; ++d) { CONV_HEADT(); CONV_TILESTEP(0, CONV_BPH(0, 0, d + 1), CONV_BPH(0, 1, d + 1), 1, CONV_WB(step + 1), 3, 1); CONV_TAIL(); }
;     for (int d = CONV_DS(lo1); d < lo1 + hw; ++d) { CONV_HEADT(); CONV_TILESTEP(0, CONV_BPH(1, 0, d), CONV_BPH(1, 1, d), 0, Wn, 3, 1);
;       CONV_TILESTEP(1, CONV_NB1(0), CONV_NB1(1), 1, CONV_WB(step + 1), 1, 0); CONV_TAIL(); }
.LBB0_415:
	s_setprio 1
	v_lshl_add_u32 v240, v100, 1, v227
	global_load_dword v230, v240, s[8:9] offset:-2048
	global_load_dword v231, v240, s[8:9] offset:-1920
	global_load_dword v238, v240, s[8:9] offset:-1792
	global_load_dword v239, v240, s[8:9] offset:-1664
	v_add3_u32 v83, v247, s17, 1
	s_add_i32 s69, s61, s16
	s_add_i32 s68, s69, -1
	s_waitcnt lgkmcnt(1)
	v_mfma_f32_16x16x32_bf16 v[2:5], v[72:75], v[144:147], v[16:19]
	v_mfma_f32_16x16x32_bf16 v[16:19], v[64:67], v[144:147], v[20:23]
	v_mfma_f32_16x16x32_bf16 v[12:15], v[88:91], v[144:147], v[12:15]
	v_mfma_f32_16x16x32_bf16 v[6:9], v[76:79], v[144:147], v[8:11]
	s_waitcnt lgkmcnt(0)
	v_mfma_f32_16x16x32_bf16 v[20:23], v[72:75], v[128:131], v[52:55]
	v_mfma_f32_16x16x32_bf16 v[48:51], v[64:67], v[128:131], v[48:51]
	v_mfma_f32_16x16x32_bf16 v[44:47], v[88:91], v[128:131], v[44:47]
	v_mfma_f32_16x16x32_bf16 v[40:43], v[76:79], v[128:131], v[40:43]
	v_mfma_f32_16x16x32_bf16 v[52:55], v[56:59], v[140:143], v[2:5]
	v_mfma_f32_16x16x32_bf16 v[4:7], v[64:67], v[140:143], v[6:9]
	v_mfma_f32_16x16x32_bf16 v[20:23], v[56:59], v[124:127], v[20:23]
	v_mfma_f32_16x16x32_bf16 v[10:13], v[72:75], v[140:143], v[12:15]
	v_mfma_f32_16x16x32_bf16 v[48:51], v[60:63], v[124:127], v[48:51]
	v_mfma_f32_16x16x32_bf16 v[44:47], v[72:75], v[124:127], v[44:47]
	v_mfma_f32_16x16x32_bf16 v[40:43], v[64:67], v[124:127], v[40:43]
	v_mfma_f32_16x16x32_bf16 v[106:109], v[60:63], v[136:139], v[4:7]
	v_cmp_gt_u32_e32 vcc, s61, v83
	v_mov_b32_e32 v83, s29
	s_nop 0
	v_cndmask_b32_e32 v130, v83, v82, vcc
	v_mfma_f32_16x16x32_bf16 v[16:19], v[60:63], v[140:143], v[16:19]
	v_mfma_f32_16x16x32_bf16 v[52:55], v[28:31], v[136:139], v[52:55]
	v_mfma_f32_16x16x32_bf16 v[48:51], v[24:27], v[120:123], v[48:51]
	v_mfma_f32_16x16x32_bf16 v[44:47], v[56:59], v[120:123], v[44:47]
	v_mfma_f32_16x16x32_bf16 v[8:11], v[56:59], v[136:139], v[10:13]
	v_mfma_f32_16x16x32_bf16 v[12:15], v[28:31], v[132:135], v[8:11]
	v_mfma_f32_16x16x32_bf16 v[8:11], v[24:27], v[132:135], v[106:109]
	s_nop 2
	ds_read_b128 v[106:109], v130 offset:64
	v_mfma_f32_16x16x32_bf16 v[102:105], v[24:27], v[136:139], v[16:19]
	v_mfma_f32_16x16x32_bf16 v[124:127], v[28:31], v[120:123], v[20:23]
	v_mfma_f32_16x16x32_bf16 v[40:43], v[60:63], v[120:123], v[40:43]
	ds_read_b128 v[110:113], v130 offset:128
	v_mfma_f32_16x16x32_bf16 v[16:19], v[32:35], v[132:135], v[52:55]
	v_mfma_f32_16x16x32_bf16 v[20:23], v[36:39], v[132:135], v[102:105]
	ds_read_b128 v[120:123], v130 offset:192
	v_mfma_f32_16x16x32_bf16 v[52:55], v[32:35], v[116:119], v[124:127]
	v_mfma_f32_16x16x32_bf16 v[48:51], v[36:39], v[116:119], v[48:51]
	v_mfma_f32_16x16x32_bf16 v[44:47], v[28:31], v[116:119], v[44:47]
	v_mfma_f32_16x16x32_bf16 v[40:43], v[24:27], v[116:119], v[40:43]
	ds_read_b128 v[102:105], v130
	s_setprio 0
	s_setprio 1
	s_cmp_lt_i32 s16, s26
	s_cselect_b64 vcc, -1, 0
	v_cndmask_b32_e32 v80, v247, v242, vcc
	v_add_u32_e32 v80, s17, v80
	v_cndmask_b32_e32 v101, v248, v245, vcc
	v_cmp_gt_u32_e64 s[0:1], s61, v80
	v_mad_u64_u32 v[114:115], s[70:71], v80, s85, v[156:157]
	v_add_u32_e32 v101, s17, v101
	v_cndmask_b32_e64 v80, v83, v114, s[0:1]
	v_mad_u64_u32 v[114:115], s[0:1], v101, s85, v[156:157]
	s_and_b32 s0, s69, 7
	v_cmp_gt_u32_e32 vcc, s61, v101
	s_mulk_i32 s0, 0x1200
	v_add_u32_e32 v101, s0, v243
	v_cndmask_b32_e32 v83, v83, v114, vcc
	s_waitcnt lgkmcnt(0)
	v_mfma_f32_16x16x32_bf16 v[92:95], v[72:75], v[102:105], v[92:95]
	v_mfma_f32_16x16x32_bf16 v[96:99], v[64:67], v[102:105], v[96:99]
	v_mfma_f32_16x16x32_bf16 v[84:87], v[88:91], v[102:105], v[84:87]
	v_mfma_f32_16x16x32_bf16 v[68:71], v[76:79], v[102:105], v[68:71]
	ds_read_b128 v[144:147], v80
	v_mfma_f32_16x16x32_bf16 v[92:95], v[56:59], v[106:109], v[92:95]
	v_mfma_f32_16x16x32_bf16 v[96:99], v[60:63], v[106:109], v[96:99]
	v_mfma_f32_16x16x32_bf16 v[72:75], v[72:75], v[106:109], v[84:87]
	v_mfma_f32_16x16x32_bf16 v[64:67], v[64:67], v[106:109], v[68:71]
	ds_read_b128 v[128:131], v83
	ds_read_b128 v[76:79], v101 offset:160
	ds_read_b128 v[88:91], v101 offset:192
	v_mfma_f32_16x16x32_bf16 v[68:71], v[28:31], v[110:113], v[92:95]
	v_mfma_f32_16x16x32_bf16 v[84:87], v[24:27], v[110:113], v[96:99]
	v_mfma_f32_16x16x32_bf16 v[56:59], v[56:59], v[110:113], v[72:75]
	v_mfma_f32_16x16x32_bf16 v[60:63], v[60:63], v[110:113], v[64:67]
	ds_read_b128 v[140:143], v80 offset:64
	v_mfma_f32_16x16x32_bf16 v[92:95], v[32:35], v[120:123], v[68:71]
	v_mfma_f32_16x16x32_bf16 v[96:99], v[36:39], v[120:123], v[84:87]
	v_mfma_f32_16x16x32_bf16 v[84:87], v[28:31], v[120:123], v[56:59]
	v_mfma_f32_16x16x32_bf16 v[68:71], v[24:27], v[120:123], v[60:63]
	ds_read_b128 v[124:127], v83 offset:64
	ds_read_b128 v[64:67], v101 offset:224
	ds_read_b128 v[72:75], v101 offset:256
	ds_read_b128 v[136:139], v80 offset:128
	ds_read_b128 v[120:123], v83 offset:128
	ds_read_b128 v[60:63], v101 offset:288
	ds_read_b128 v[56:59], v101 offset:320
	ds_read_b128 v[132:135], v80 offset:192
	ds_read_b128 v[116:119], v83 offset:192
	ds_read_b128 v[24:27], v101 offset:352
	ds_read_b128 v[28:31], v101 offset:384
	ds_read_b128 v[36:39], v101 offset:416
	ds_read_b128 v[32:35], v101 offset:448
	s_setprio 0
	s_add_i32 s0, s69, 3
	s_cmp_ge_i32 s0, s87
	s_cbranch_scc1 .LBB0_417
	s_and_b32 s0, s0, 4
	s_and_b32 s1, s68, 3
	s_or_b32 s0, s0, s1
	s_mulk_i32 s0, 0x1200
	v_add_u32_e32 v80, s0, v157
	s_waitcnt vmcnt(0)
	ds_write2_b32 v80, v230, v231 offset1:32
	ds_write2_b32 v80, v238, v239 offset0:64 offset1:96

; #define CONV_TAIL() if (step + CONV_GRP < nsteps) CONV_STOREWIN(step + CONV_GRP); if ((step & 1) == 1 || step + 1 == nsteps) __syncthreads()
; #define CONV_DS(x) ({ int t_ = (x); LAUNDER_S(t_); t_; })
; #define CONV_NB1(H) ((d + 1 <= hi0) ? CONV_BPH(0, H, d + 1) : CONV_BPH(1, H, d + 1))
; __device__ __forceinline__ void conv_item(const Params& P, int slice, int item, LAS unsigned char* lds) {
;     ...
;     for (int d = CONV_DS(lo1 + hw); d <= hi0 - hw; ++d) { CONV_HEADT(); CONV_TILESTEP(0, CONV_BPH(1, 0, d), CONV_BPH(1, 1, d), 0, Wn, 3, 1);
;       CONV_TILESTEP(1, CONV_NB1(0), CONV_NB1(1), 1, CONV_WB(step + 1), 3, 0); CONV_TAIL(); }
.LBB0_422:
	s_add_i32 s68, s17, 1
	s_setprio 1
	v_lshl_add_u32 v240, v150, 1, v227
	global_load_dword v230, v240, s[8:9] offset:-2048
	global_load_dword v231, v240, s[8:9] offset:-1920
	global_load_dword v238, v240, s[8:9] offset:-1792
	global_load_dword v239, v240, s[8:9] offset:-1664
	v_add3_u32 v83, v247, s16, 1
	v_add3_u32 v149, v248, s16, 1
	s_add_i32 s69, s61, s17
	s_waitcnt lgkmcnt(1)
	v_mfma_f32_16x16x32_bf16 v[16:19], v[72:75], v[144:147], v[16:19]
	v_mfma_f32_16x16x32_bf16 v[20:23], v[64:67], v[144:147], v[20:23]
	v_mfma_f32_16x16x32_bf16 v[12:15], v[88:91], v[144:147], v[12:15]
	v_mfma_f32_16x16x32_bf16 v[8:11], v[76:79], v[144:147], v[8:11]
	s_waitcnt lgkmcnt(0)
	v_mfma_f32_16x16x32_bf16 v[52:55], v[72:75], v[128:131], v[52:55]
	v_mfma_f32_16x16x32_bf16 v[48:51], v[64:67], v[128:131], v[48:51]
	v_mfma_f32_16x16x32_bf16 v[44:47], v[88:91], v[128:131], v[44:47]
	v_mfma_f32_16x16x32_bf16 v[40:43], v[76:79], v[128:131], v[40:43]
	v_mfma_f32_16x16x32_bf16 v[40:43], v[64:67], v[124:127], v[40:43]
	v_mfma_f32_16x16x32_bf16 v[40:43], v[60:63], v[120:123], v[40:43]
	v_mfma_f32_16x16x32_bf16 v[40:43], v[24:27], v[116:119], v[40:43]
	v_mfma_f32_16x16x32_bf16 v[44:47], v[72:75], v[124:127], v[44:47]
	v_mfma_f32_16x16x32_bf16 v[44:47], v[56:59], v[120:123], v[44:47]
	v_mfma_f32_16x16x32_bf16 v[44:47], v[28:31], v[116:119], v[44:47]
	v_mfma_f32_16x16x32_bf16 v[48:51], v[60:63], v[124:127], v[48:51]
	v_mfma_f32_16x16x32_bf16 v[48:51], v[24:27], v[120:123], v[48:51]
	v_mfma_f32_16x16x32_bf16 v[48:51], v[36:39], v[116:119], v[48:51]
	v_mfma_f32_16x16x32_bf16 v[52:55], v[56:59], v[124:127], v[52:55]
	v_mfma_f32_16x16x32_bf16 v[52:55], v[28:31], v[120:123], v[52:55]
	v_mfma_f32_16x16x32_bf16 v[52:55], v[32:35], v[116:119], v[52:55]
	v_mov_b32_e32 v80, s29
	v_cmp_gt_u32_e32 vcc, s61, v83
	s_nop 1
	v_cndmask_b32_e32 v83, v80, v148, vcc
	v_cmp_gt_u32_e32 vcc, s61, v149
	s_nop 1
	v_cndmask_b32_e32 v149, v80, v82, vcc
	ds_read_b128 v[116:119], v149 offset:192
	v_mfma_f32_16x16x32_bf16 v[8:11], v[64:67], v[140:143], v[8:11]
	v_mfma_f32_16x16x32_bf16 v[16:19], v[56:59], v[140:143], v[16:19]
	v_mfma_f32_16x16x32_bf16 v[20:23], v[60:63], v[140:143], v[20:23]
	v_mfma_f32_16x16x32_bf16 v[12:15], v[72:75], v[140:143], v[12:15]
	v_mfma_f32_16x16x32_bf16 v[8:11], v[60:63], v[136:139], v[8:11]
	v_mfma_f32_16x16x32_bf16 v[8:11], v[24:27], v[132:135], v[8:11]
	v_mfma_f32_16x16x32_bf16 v[12:15], v[56:59], v[136:139], v[12:15]
	v_mfma_f32_16x16x32_bf16 v[12:15], v[28:31], v[132:135], v[12:15]
	v_mfma_f32_16x16x32_bf16 v[20:23], v[24:27], v[136:139], v[20:23]
	v_mfma_f32_16x16x32_bf16 v[20:23], v[36:39], v[132:135], v[20:23]
	v_mfma_f32_16x16x32_bf16 v[16:19], v[28:31], v[136:139], v[16:19]
	v_mfma_f32_16x16x32_bf16 v[16:19], v[32:35], v[132:135], v[16:19]
	ds_read_b128 v[132:135], v83 offset:192
	ds_read_b128 v[120:123], v149 offset:128
	ds_read_b128 v[136:139], v83 offset:128
	ds_read_b128 v[124:127], v149 offset:64
	ds_read_b128 v[140:143], v83 offset:64
	ds_read_b128 v[128:131], v149
	ds_read_b128 v[144:147], v83
	s_setprio 0
	s_setprio 1
	s_cmp_lt_i32 s68, s26
	s_cselect_b64 vcc, -1, 0
	v_cndmask_b32_e32 v83, v247, v242, vcc
	v_add_u32_e32 v83, s16, v83
	v_cndmask_b32_e32 v149, v248, v245, vcc
	v_cmp_gt_u32_e64 s[0:1], s61, v83
	v_mad_u64_u32 v[152:153], s[70:71], v83, s85, v[156:157]
	v_add_u32_e32 v149, s16, v149
	v_cndmask_b32_e64 v83, v80, v152, s[0:1]
	v_mad_u64_u32 v[152:153], s[0:1], v149, s85, v[156:157]
	s_add_i32 s0, s69, 1
	s_and_b32 s0, s0, 7
	v_cmp_gt_u32_e32 vcc, s61, v149
	s_mulk_i32 s0, 0x1200
	v_add_u32_e32 v149, s0, v243
	v_cndmask_b32_e32 v80, v80, v152, vcc
	s_waitcnt lgkmcnt(0)
	v_mfma_f32_16x16x32_bf16 v[92:95], v[72:75], v[144:147], v[92:95]
	v_mfma_f32_16x16x32_bf16 v[96:99], v[64:67], v[144:147], v[96:99]
	v_mfma_f32_16x16x32_bf16 v[84:87], v[88:91], v[144:147], v[84:87]
	v_mfma_f32_16x16x32_bf16 v[68:71], v[76:79], v[144:147], v[68:71]
	ds_read_b128 v[144:147], v83
	v_mfma_f32_16x16x32_bf16 v[112:115], v[72:75], v[128:131], v[112:115]
	v_mfma_f32_16x16x32_bf16 v[108:111], v[64:67], v[128:131], v[108:111]
	v_mfma_f32_16x16x32_bf16 v[104:107], v[88:91], v[128:131], v[104:107]
	v_mfma_f32_16x16x32_bf16 v[100:103], v[76:79], v[128:131], v[100:103]
	ds_read_b128 v[128:131], v80
	ds_read_b128 v[76:79], v149 offset:160
	ds_read_b128 v[88:91], v149 offset:192
	v_mfma_f32_16x16x32_bf16 v[92:95], v[56:59], v[140:143], v[92:95]
	v_mfma_f32_16x16x32_bf16 v[96:99], v[60:63], v[140:143], v[96:99]
	v_mfma_f32_16x16x32_bf16 v[84:87], v[72:75], v[140:143], v[84:87]
	v_mfma_f32_16x16x32_bf16 v[68:71], v[64:67], v[140:143], v[68:71]
	ds_read_b128 v[140:143], v83 offset:64
	v_mfma_f32_16x16x32_bf16 v[112:115], v[56:59], v[124:127], v[112:115]
	v_mfma_f32_16x16x32_bf16 v[108:111], v[60:63], v[124:127], v[108:111]
	v_mfma_f32_16x16x32_bf16 v[104:107], v[72:75], v[124:127], v[104:107]
	v_mfma_f32_16x16x32_bf16 v[100:103], v[64:67], v[124:127], v[100:103]
	ds_read_b128 v[124:127], v80 offset:64
	ds_read_b128 v[64:67], v149 offset:224
	ds_read_b128 v[72:75], v149 offset:256
	v_mfma_f32_16x16x32_bf16 v[92:95], v[28:31], v[136:139], v[92:95]
	v_mfma_f32_16x16x32_bf16 v[96:99], v[24:27], v[136:139], v[96:99]
	v_mfma_f32_16x16x32_bf16 v[84:87], v[56:59], v[136:139], v[84:87]
	v_mfma_f32_16x16x32_bf16 v[68:71], v[60:63], v[136:139], v[68:71]
	ds_read_b128 v[136:139], v83 offset:128
	v_mfma_f32_16x16x32_bf16 v[112:115], v[28:31], v[120:123], v[112:115]
	v_mfma_f32_16x16x32_bf16 v[108:111], v[24:27], v[120:123], v[108:111]
	v_mfma_f32_16x16x32_bf16 v[104:107], v[56:59], v[120:123], v[104:107]
	v_mfma_f32_16x16x32_bf16 v[100:103], v[60:63], v[120:123], v[100:103]
	ds_read_b128 v[120:123], v80 offset:128
	ds_read_b128 v[60:63], v149 offset:288
	ds_read_b128 v[56:59], v149 offset:320
	v_mfma_f32_16x16x32_bf16 v[92:95], v[32:35], v[132:135], v[92:95]
	v_mfma_f32_16x16x32_bf16 v[96:99], v[36:39], v[132:135], v[96:99]
	v_mfma_f32_16x16x32_bf16 v[84:87], v[28:31], v[132:135], v[84:87]
	v_mfma_f32_16x16x32_bf16 v[68:71], v[24:27], v[132:135], v[68:71]
	ds_read_b128 v[132:135], v83 offset:192
	v_mfma_f32_16x16x32_bf16 v[112:115], v[32:35], v[116:119], v[112:115]
	v_mfma_f32_16x16x32_bf16 v[108:111], v[36:39], v[116:119], v[108:111]
	v_mfma_f32_16x16x32_bf16 v[104:107], v[28:31], v[116:119], v[104:107]
	v_mfma_f32_16x16x32_bf16 v[100:103], v[24:27], v[116:119], v[100:103]
	ds_read_b128 v[116:119], v80 offset:192
	ds_read_b128 v[24:27], v149 offset:352
	ds_read_b128 v[28:31], v149 offset:384
	ds_read_b128 v[36:39], v149 offset:416
	ds_read_b128 v[32:35], v149 offset:448
	s_setprio 0
	s_add_i32 s0, s69, 4
	s_cmp_ge_i32 s0, s87
	s_cbranch_scc1 .LBB0_424
	s_and_b32 s0, s0, 4
	s_and_b32 s1, s69, 3
	s_or_b32 s0, s0, s1
	s_mulk_i32 s0, 0x1200
	v_add_u32_e32 v80, s0, v157
	s_waitcnt vmcnt(0)
	ds_write2_b32 v80, v230, v231 offset1:32
	ds_write2_b32 v80, v238, v239 offset0:64 offset1:96

; #define CONV_TAIL() if (step + CONV_GRP < nsteps) CONV_STOREWIN(step + CONV_GRP); if ((step & 1) == 1 || step + 1 == nsteps) __syncthreads()
; #define CONV_DS(x) ({ int t_ = (x); LAUNDER_S(t_); t_; })
; #define CONV_NB1(H) ((d + 1 <= hi0) ? CONV_BPH(0, H, d + 1) : CONV_BPH(1, H, d + 1))
; __device__ __forceinline__ void conv_item(const Params& P, int slice, int item, LAS unsigned char* lds) {
;     ...
;     for (int d = CONV_DS(hi0 - hw + 1); d <= hi0; ++d) { CONV_HEADT(); CONV_TILESTEP(0, CONV_BPH(1, 0, d), CONV_BPH(1, 1, d), 0, Wn, 2, 1);
;       CONV_TILESTEP(1, CONV_NB1(0), CONV_NB1(1), 1, CONV_WB(step + 1), 3, 0); CONV_TAIL(); }
.LBB0_432:
	s_setprio 1
	v_lshl_add_u32 v240, v233, 1, v227
	global_load_dword v230, v240, s[8:9] offset:-2048
	global_load_dword v231, v240, s[8:9] offset:-1920
	global_load_dword v238, v240, s[8:9] offset:-1792
	global_load_dword v239, v240, s[8:9] offset:-1664
	v_add3_u32 v1, v247, s69, 1
	v_add3_u32 v6, v248, s69, 1
	s_add_i32 s71, s61, s68
	s_add_i32 s70, s71, -1
	s_waitcnt lgkmcnt(0)
	v_mfma_f32_16x16x32_bf16 v[2:5], v[72:75], v[128:131], v[52:55]
	v_mfma_f32_16x16x32_bf16 v[48:51], v[64:67], v[128:131], v[48:51]
	v_mfma_f32_16x16x32_bf16 v[44:47], v[88:91], v[128:131], v[44:47]
	v_mfma_f32_16x16x32_bf16 v[40:43], v[76:79], v[128:131], v[40:43]
	v_mov_b32_e32 v83, s29
	v_cmp_gt_u32_e32 vcc, s61, v1
	s_nop 1
	v_cndmask_b32_e32 v130, v83, v216, vcc
	v_cmp_gt_u32_e32 vcc, s61, v6
	s_nop 1
	v_cndmask_b32_e32 v138, v83, v82, vcc
	v_mfma_f32_16x16x32_bf16 v[2:5], v[56:59], v[124:127], v[2:5]
	v_mfma_f32_16x16x32_bf16 v[48:51], v[60:63], v[124:127], v[48:51]
	v_mfma_f32_16x16x32_bf16 v[44:47], v[72:75], v[124:127], v[44:47]
	v_mfma_f32_16x16x32_bf16 v[40:43], v[64:67], v[124:127], v[40:43]
	v_mfma_f32_16x16x32_bf16 v[48:51], v[24:27], v[120:123], v[48:51]
	v_mfma_f32_16x16x32_bf16 v[44:47], v[56:59], v[120:123], v[44:47]
	v_mfma_f32_16x16x32_bf16 v[40:43], v[60:63], v[120:123], v[40:43]
	v_mfma_f32_16x16x32_bf16 v[48:51], v[36:39], v[116:119], v[48:51]
	ds_read_b128 v[148:151], v138 offset:192
	v_mfma_f32_16x16x32_bf16 v[4:7], v[28:31], v[120:123], v[2:5]
	v_mfma_f32_16x16x32_bf16 v[44:47], v[28:31], v[116:119], v[44:47]
	v_mfma_f32_16x16x32_bf16 v[40:43], v[24:27], v[116:119], v[40:43]
	s_nop 0
	v_mfma_f32_16x16x32_bf16 v[52:55], v[32:35], v[116:119], v[4:7]
	ds_read_b128 v[116:119], v138 offset:128
	ds_read_b128 v[124:127], v138 offset:64
	ds_read_b128 v[136:139], v138
	ds_read_b128 v[132:135], v130 offset:64
	ds_read_b128 v[152:155], v130 offset:192
	ds_read_b128 v[120:123], v130 offset:128
	ds_read_b128 v[128:131], v130
	s_setprio 0
	s_setprio 1
	s_cmp_ge_i32 s68, s26
	s_cselect_b64 s[16:17], -1, 0
	s_cmp_lt_i32 s68, s26
	s_cselect_b64 vcc, -1, 0
	v_cndmask_b32_e32 v80, v247, v242, vcc
	v_add_u32_e32 v80, s69, v80
	v_cmp_gt_u32_e64 s[0:1], s61, v80
	v_mad_u64_u32 v[140:141], s[72:73], v80, s85, v[156:157]
	s_nop 0
	v_cndmask_b32_e64 v80, v83, v140, s[0:1]
	v_cndmask_b32_e32 v140, v248, v245, vcc
	v_add_u32_e32 v140, s69, v140
	v_cmp_gt_u32_e32 vcc, s61, v140
	v_mad_u64_u32 v[140:141], s[0:1], v140, s85, v[156:157]
	s_and_b32 s0, s71, 7
	s_mulk_i32 s0, 0x1200
	v_cndmask_b32_e32 v83, v83, v140, vcc
	v_add_u32_e32 v217, s0, v243
	s_waitcnt lgkmcnt(0)
	v_mfma_f32_16x16x32_bf16 v[92:95], v[72:75], v[128:131], v[92:95]
	v_mfma_f32_16x16x32_bf16 v[96:99], v[64:67], v[128:131], v[96:99]
	v_mfma_f32_16x16x32_bf16 v[84:87], v[88:91], v[128:131], v[84:87]
	v_mfma_f32_16x16x32_bf16 v[68:71], v[76:79], v[128:131], v[68:71]
	ds_read_b128 v[144:147], v80
	v_mfma_f32_16x16x32_bf16 v[112:115], v[72:75], v[136:139], v[112:115]
	v_mfma_f32_16x16x32_bf16 v[108:111], v[64:67], v[136:139], v[108:111]
	v_mfma_f32_16x16x32_bf16 v[104:107], v[88:91], v[136:139], v[104:107]
	v_mfma_f32_16x16x32_bf16 v[100:103], v[76:79], v[136:139], v[100:103]
	ds_read_b128 v[128:131], v83
	ds_read_b128 v[76:79], v217 offset:160
	ds_read_b128 v[88:91], v217 offset:192
	v_mfma_f32_16x16x32_bf16 v[92:95], v[56:59], v[132:135], v[92:95]
	v_mfma_f32_16x16x32_bf16 v[96:99], v[60:63], v[132:135], v[96:99]
	v_mfma_f32_16x16x32_bf16 v[84:87], v[72:75], v[132:135], v[84:87]
	v_mfma_f32_16x16x32_bf16 v[68:71], v[64:67], v[132:135], v[68:71]
	ds_read_b128 v[140:143], v80 offset:64
	v_mfma_f32_16x16x32_bf16 v[112:115], v[56:59], v[124:127], v[112:115]
	v_mfma_f32_16x16x32_bf16 v[108:111], v[60:63], v[124:127], v[108:111]
	v_mfma_f32_16x16x32_bf16 v[104:107], v[72:75], v[124:127], v[104:107]
	v_mfma_f32_16x16x32_bf16 v[100:103], v[64:67], v[124:127], v[100:103]
	ds_read_b128 v[124:127], v83 offset:64
	ds_read_b128 v[64:67], v217 offset:224
	ds_read_b128 v[72:75], v217 offset:256
	v_mfma_f32_16x16x32_bf16 v[92:95], v[28:31], v[120:123], v[92:95]
	v_mfma_f32_16x16x32_bf16 v[96:99], v[24:27], v[120:123], v[96:99]
	v_mfma_f32_16x16x32_bf16 v[84:87], v[56:59], v[120:123], v[84:87]
	v_mfma_f32_16x16x32_bf16 v[68:71], v[60:63], v[120:123], v[68:71]
	ds_read_b128 v[136:139], v80 offset:128
	v_mfma_f32_16x16x32_bf16 v[112:115], v[28:31], v[116:119], v[112:115]
	v_mfma_f32_16x16x32_bf16 v[108:111], v[24:27], v[116:119], v[108:111]
	v_mfma_f32_16x16x32_bf16 v[104:107], v[56:59], v[116:119], v[104:107]
	v_mfma_f32_16x16x32_bf16 v[100:103], v[60:63], v[116:119], v[100:103]
	ds_read_b128 v[120:123], v83 offset:128
	ds_read_b128 v[60:63], v217 offset:288
	ds_read_b128 v[56:59], v217 offset:320
	v_mfma_f32_16x16x32_bf16 v[92:95], v[32:35], v[152:155], v[92:95]
	v_mfma_f32_16x16x32_bf16 v[96:99], v[36:39], v[152:155], v[96:99]
	v_mfma_f32_16x16x32_bf16 v[84:87], v[28:31], v[152:155], v[84:87]
	v_mfma_f32_16x16x32_bf16 v[68:71], v[24:27], v[152:155], v[68:71]
	ds_read_b128 v[132:135], v80 offset:192
	v_mfma_f32_16x16x32_bf16 v[112:115], v[32:35], v[148:151], v[112:115]
	v_mfma_f32_16x16x32_bf16 v[108:111], v[36:39], v[148:151], v[108:111]
	v_mfma_f32_16x16x32_bf16 v[104:107], v[28:31], v[148:151], v[104:107]
	v_mfma_f32_16x16x32_bf16 v[100:103], v[24:27], v[148:151], v[100:103]
	ds_read_b128 v[116:119], v83 offset:192
	ds_read_b128 v[24:27], v217 offset:352
	ds_read_b128 v[28:31], v217 offset:384
	ds_read_b128 v[36:39], v217 offset:416
	ds_read_b128 v[32:35], v217 offset:448
	s_setprio 0
	s_add_i32 s0, s71, 3
	s_cmp_ge_i32 s0, s87
	s_cbranch_scc1 .LBB0_434
	s_and_b32 s0, s0, 4
	s_and_b32 s1, s70, 3
	s_or_b32 s0, s0, s1
	s_mulk_i32 s0, 0x1200
	v_add_u32_e32 v80, s0, v157
	s_waitcnt vmcnt(0)
	ds_write2_b32 v80, v230, v231 offset1:32
	ds_write2_b32 v80, v238, v239 offset0:64 offset1:96

; #define CONV_TAIL() if (step + CONV_GRP < nsteps) CONV_STOREWIN(step + CONV_GRP); if ((step & 1) == 1 || step + 1 == nsteps) __syncthreads()
; #define CONV_DS(x) ({ int t_ = (x); LAUNDER_S(t_); t_; })
; __device__ __forceinline__ void conv_item(const Params& P, int slice, int item, LAS unsigned char* lds) {
;     ...
;     for (int d = CONV_DS(hi0 + 1); d <= hi1 - hw; ++d) { CONV_HEADT(); CONV_TILESTEP(1, CONV_BPH(1, 0, d + 1), CONV_BPH(1, 1, d + 1), 1, CONV_WB(step + 1), 3, 1); CONV_TAIL(); }
.LBB0_439:
	s_add_i32 s17, s61, s16
	s_setprio 1
	v_lshl_add_u32 v240, v82, 1, v227
	global_load_dword v230, v240, s[8:9] offset:-2048
	global_load_dword v231, v240, s[8:9] offset:-1920
	global_load_dword v238, v240, s[8:9] offset:-1792
	global_load_dword v239, v240, s[8:9] offset:-1664
	v_add_u32_e32 v154, s30, v83
	s_add_i32 s0, s17, 1
	s_and_b32 s0, s0, 7
	s_mulk_i32 s0, 0x1200
	s_waitcnt lgkmcnt(1)
	v_mfma_f32_16x16x32_bf16 v[0:3], v[72:75], v[144:147], v[92:95]
	v_mfma_f32_16x16x32_bf16 v[4:7], v[64:67], v[144:147], v[96:99]
	v_mfma_f32_16x16x32_bf16 v[84:87], v[88:91], v[144:147], v[84:87]
	v_mfma_f32_16x16x32_bf16 v[68:71], v[76:79], v[144:147], v[68:71]
	s_waitcnt lgkmcnt(0)
	v_mfma_f32_16x16x32_bf16 v[92:95], v[72:75], v[128:131], v[112:115]
	v_mfma_f32_16x16x32_bf16 v[0:3], v[56:59], v[140:143], v[0:3]
	v_mfma_f32_16x16x32_bf16 v[92:95], v[56:59], v[124:127], v[92:95]
	v_mfma_f32_16x16x32_bf16 v[0:3], v[28:31], v[136:139], v[0:3]
	v_mfma_f32_16x16x32_bf16 v[96:99], v[28:31], v[120:123], v[92:95]
	v_mfma_f32_16x16x32_bf16 v[92:95], v[32:35], v[132:135], v[0:3]
	v_mfma_f32_16x16x32_bf16 v[112:115], v[32:35], v[116:119], v[96:99]
	v_mfma_f32_16x16x32_bf16 v[96:99], v[64:67], v[128:131], v[108:111]
	s_nop 3
	v_mfma_f32_16x16x32_bf16 v[88:91], v[88:91], v[128:131], v[104:107]
	v_mfma_f32_16x16x32_bf16 v[84:87], v[72:75], v[140:143], v[84:87]
	v_mfma_f32_16x16x32_bf16 v[72:75], v[72:75], v[124:127], v[88:91]
	v_mfma_f32_16x16x32_bf16 v[76:79], v[76:79], v[128:131], v[100:103]
	v_mfma_f32_16x16x32_bf16 v[84:87], v[56:59], v[136:139], v[84:87]
	v_mfma_f32_16x16x32_bf16 v[56:59], v[56:59], v[120:123], v[72:75]
	v_mfma_f32_16x16x32_bf16 v[84:87], v[28:31], v[132:135], v[84:87]
	v_mfma_f32_16x16x32_bf16 v[104:107], v[28:31], v[116:119], v[56:59]
	s_nop 1
	s_nop 0
	v_mov_b32_e32 v72, s29
	v_mfma_f32_16x16x32_bf16 v[2:5], v[60:63], v[140:143], v[4:7]
	v_mfma_f32_16x16x32_bf16 v[56:59], v[60:63], v[124:127], v[96:99]
	v_mfma_f32_16x16x32_bf16 v[2:5], v[24:27], v[136:139], v[2:5]
	v_mfma_f32_16x16x32_bf16 v[56:59], v[24:27], v[120:123], v[56:59]
	v_mfma_f32_16x16x32_bf16 v[96:99], v[36:39], v[132:135], v[2:5]
	v_mfma_f32_16x16x32_bf16 v[2:5], v[64:67], v[140:143], v[68:71]
	v_mfma_f32_16x16x32_bf16 v[108:111], v[36:39], v[116:119], v[56:59]
	v_mfma_f32_16x16x32_bf16 v[56:59], v[64:67], v[124:127], v[76:79]
	v_mfma_f32_16x16x32_bf16 v[2:5], v[60:63], v[136:139], v[2:5]
	v_mfma_f32_16x16x32_bf16 v[68:71], v[24:27], v[132:135], v[2:5]
	s_nop 6
	v_mfma_f32_16x16x32_bf16 v[56:59], v[60:63], v[120:123], v[56:59]
	v_mfma_f32_16x16x32_bf16 v[100:103], v[24:27], v[116:119], v[56:59]
	s_nop 6
	v_cmp_gt_u32_e32 vcc, s61, v83
	s_nop 1
	v_cndmask_b32_e32 v136, v72, v149, vcc
	ds_read_b128 v[140:143], v136 offset:64
	ds_read_b128 v[144:147], v136
	ds_read_b128 v[132:135], v136 offset:192
	ds_read_b128 v[136:139], v136 offset:128
	v_add_u32_e32 v155, s0, v243
	v_cmp_gt_u32_e64 s[0:1], s61, v154
	s_nop 1
	v_cndmask_b32_e64 v74, v72, v148, s[0:1]
	ds_read_b128 v[88:91], v155 offset:192
	ds_read_b128 v[124:127], v74 offset:64
	ds_read_b128 v[120:123], v74 offset:128
	ds_read_b128 v[128:131], v74
	ds_read_b128 v[116:119], v74 offset:192
	ds_read_b128 v[72:75], v155 offset:256
	ds_read_b128 v[32:35], v155 offset:448
	ds_read_b128 v[76:79], v155 offset:160
	ds_read_b128 v[28:31], v155 offset:384
	ds_read_b128 v[64:67], v155 offset:224
	ds_read_b128 v[36:39], v155 offset:416
	ds_read_b128 v[24:27], v155 offset:352
	ds_read_b128 v[60:63], v155 offset:288
	ds_read_b128 v[56:59], v155 offset:320
	s_setprio 0
	s_add_i32 s0, s17, 4
	s_cmp_ge_i32 s0, s87
	s_cbranch_scc1 .LBB0_441
	s_and_b32 s0, s0, 4
	s_and_b32 s1, s17, 3
	s_or_b32 s0, s0, s1
	s_mulk_i32 s0, 0x1200
	v_add_u32_e32 v80, s0, v157
	s_waitcnt vmcnt(0)
	ds_write2_b32 v80, v230, v231 offset1:32
	ds_write2_b32 v80, v238, v239 offset0:64 offset1:96

; #define CONV_TAIL() if (step + CONV_GRP < nsteps) CONV_STOREWIN(step + CONV_GRP); if ((step & 1) == 1 || step + 1 == nsteps) __syncthreads()
; #define CONV_DS(x) ({ int t_ = (x); LAUNDER_S(t_); t_; })
; __device__ __forceinline__ void conv_item(const Params& P, int slice, int item, LAS unsigned char* lds) {
;     ...
;     for (int d = CONV_DS(hi1 - hw + 1); d <= hi1; ++d) { CONV_HEADT(); CONV_TILESTEP(1, CONV_BPH(1, 0, d + 1), CONV_BPH(1, 1, d + 1), 1, CONV_WB(step + 1), 2, 1); CONV_TAIL(); }
.LBB0_446:
	s_add_i32 s17, s61, s16
	s_setprio 1
	v_lshl_add_u32 v240, v82, 1, v227
	global_load_dword v230, v240, s[8:9] offset:-2048
	global_load_dword v231, v240, s[8:9] offset:-1920
	global_load_dword v238, v240, s[8:9] offset:-1792
	global_load_dword v239, v240, s[8:9] offset:-1664
	s_add_i32 s0, s17, 1
	s_and_b32 s0, s0, 7
	s_mulk_i32 s0, 0x1200
	s_waitcnt lgkmcnt(0)
	v_mfma_f32_16x16x32_bf16 v[2:5], v[72:75], v[128:131], v[112:115]
	v_mfma_f32_16x16x32_bf16 v[108:111], v[64:67], v[128:131], v[108:111]
	v_mfma_f32_16x16x32_bf16 v[88:91], v[88:91], v[128:131], v[104:107]
	v_mfma_f32_16x16x32_bf16 v[76:79], v[76:79], v[128:131], v[100:103]
	v_mfma_f32_16x16x32_bf16 v[2:5], v[56:59], v[124:127], v[2:5]
	v_mfma_f32_16x16x32_bf16 v[100:103], v[60:63], v[124:127], v[108:111]
	v_mfma_f32_16x16x32_bf16 v[72:75], v[72:75], v[124:127], v[88:91]
	v_mfma_f32_16x16x32_bf16 v[64:67], v[64:67], v[124:127], v[76:79]
	v_mfma_f32_16x16x32_bf16 v[4:7], v[28:31], v[120:123], v[2:5]
	v_mfma_f32_16x16x32_bf16 v[76:79], v[24:27], v[120:123], v[100:103]
	v_mfma_f32_16x16x32_bf16 v[60:63], v[60:63], v[120:123], v[64:67]
	v_add_u32_e32 v133, s0, v243
	v_mfma_f32_16x16x32_bf16 v[112:115], v[32:35], v[116:119], v[4:7]
	v_mfma_f32_16x16x32_bf16 v[100:103], v[24:27], v[116:119], v[60:63]
	v_cmp_gt_u32_e64 s[0:1], s61, v83
	s_nop 1
	v_mov_b32_e32 v5, s29
	s_nop 0
	s_nop 1
	v_cndmask_b32_e64 v62, v5, v132, s[0:1]
	v_mfma_f32_16x16x32_bf16 v[72:75], v[56:59], v[120:123], v[72:75]
	v_mfma_f32_16x16x32_bf16 v[108:111], v[36:39], v[116:119], v[76:79]
	v_mfma_f32_16x16x32_bf16 v[104:107], v[28:31], v[116:119], v[72:75]
	ds_read_b128 v[116:119], v62 offset:192
	ds_read_b128 v[128:131], v62
	ds_read_b128 v[124:127], v62 offset:64
	ds_read_b128 v[120:123], v62 offset:128
	ds_read_b128 v[60:63], v133 offset:288
	ds_read_b128 v[56:59], v133 offset:320
	ds_read_b128 v[32:35], v133 offset:448
	ds_read_b128 v[24:27], v133 offset:352
	ds_read_b128 v[28:31], v133 offset:384
	ds_read_b128 v[36:39], v133 offset:416
	ds_read_b128 v[76:79], v133 offset:160
	ds_read_b128 v[88:91], v133 offset:192
	ds_read_b128 v[64:67], v133 offset:224
	ds_read_b128 v[72:75], v133 offset:256
	s_setprio 0
	s_add_i32 s0, s17, 4
	s_cmp_ge_i32 s0, s87
	s_cbranch_scc1 .LBB0_448
	s_and_b32 s0, s0, 4
	s_and_b32 s1, s17, 3
	s_or_b32 s0, s0, s1
	s_mulk_i32 s0, 0x1200
	v_add_u32_e32 v80, s0, v157
	s_waitcnt vmcnt(0)
	ds_write2_b32 v80, v230, v231 offset1:32
	ds_write2_b32 v80, v238, v239 offset0:64 offset1:96

; #define LAUNDER_S(x) asm volatile("" : "+s"(x))
; #define CONV_HEAD() const int step = d - dmin; if (step + CONV_GRP < nsteps) CONV_LOADWIN(d + CONV_GRP); __builtin_amdgcn_sched_barrier(0)
; #define CONV_TAIL() if (step + CONV_GRP < nsteps) CONV_STOREWIN(step + CONV_GRP); if ((step & 1) == 1 || step + 1 == nsteps) __syncthreads()
; __device__ __forceinline__ void conv_item(const Params& P, int slice, int item, LAS unsigned char* lds) {
;     ...
;     { int dl_ = hi1 + 1; LAUNDER_S(dl_); for (int d = dl_; d < nblk; ++d) { CONV_HEAD(); CONV_TAIL(); } }
.LBB0_455:
	s_add_i32 s68, s68, -1
	s_andn2_b64 vcc, exec, s[0:1]
	s_cbranch_vccnz .LBB0_457
	s_and_b32 s0, s17, 4
	s_and_b32 s1, s68, 3
	s_or_b32 s0, s0, s1
	s_mulk_i32 s0, 0x1200
	v_add_u32_e32 v25, s0, v157
	s_waitcnt vmcnt(0)
	ds_write2_b32 v25, v230, v231 offset1:32
	ds_write2_b32 v25, v238, v239 offset0:64 offset1:96
